# GEMM epilogue stores without the non-temporal hint
# speedup vs baseline: 1.0063x; 1.0063x over previous
; __device__ __forceinline__ float sigmoid_(float x) { return __builtin_amdgcn_rcpf(1.0f + __expf(-x)); }
; __device__ __forceinline__ uint4 pack8(const float (&f)[8]) { uint4 r; r.x = cvt_pk_bf16(f[0], f[1]); r.y = cvt_pk_bf16(f[2], f[3]); r.z = cvt_pk_bf16(f[4], f[5]); r.w = cvt_pk_bf16(f[6], f[7]); return r; }
; __device__ __forceinline__ void nt_store16(void* p, const uint4 v) { __builtin_nontemporal_store((u32x4){v.x, v.y, v.z, v.w}, (u32x4*)p); }
;     __device__ __forceinline__ void operator()(AccT acc, const Unit& u, int wr, int wc, int fr, int fq) const {
;     ...
;                 bf16_t* rowp = O + (size_t)(row0 + ai * HALF + m * 16) * FF_ + col0;
;                 float o[8];
; #pragma unroll
;                 for (int n = 0; n < 2; ++n)
; #pragma unroll
;                     for (int j = 0; j < 4; ++j) { const float gt = acc[ai][0][m][n][j], up = acc[ai][1][m][n][j]; o[n * 4 + j] = gt * sigmoid_(gt) * up; }
;                 nt_store16(rowp, pack8(o));
.LBB0_72:
	v_mul_f32_e32 v139, 0xbfb8aa3b, v126
	v_exp_f32_e32 v158, v139
	v_mul_f32_e32 v139, 0xbfb8aa3b, v127
	v_exp_f32_e32 v159, v139
	v_mul_f32_e32 v165, 0xbfb8aa3b, v128
	v_add_f32_e32 v158, 1.0, v158
	v_rcp_f32_e32 v166, v158
	v_add_f32_e32 v158, 1.0, v159
	v_rcp_f32_e32 v167, v158
	v_exp_f32_e32 v165, v165
	v_readlane_b32 s18, v254, 35
	v_lshl_or_b32 v138, s59, 7, v162
	v_pk_mul_f32 v[126:127], v[126:127], v[166:167]
	v_mul_f32_e32 v166, 0xbfb8aa3b, v129
	v_exp_f32_e32 v166, v166
	v_pk_mul_f32 v[122:123], v[122:123], v[126:127]
	v_add_f32_e32 v126, 1.0, v165
	v_mul_f32_e32 v165, 0xbfb8aa3b, v118
	v_add_f32_e32 v127, 1.0, v166
	v_rcp_f32_e32 v126, v126
	v_rcp_f32_e32 v127, v127
	v_exp_f32_e32 v165, v165
	v_mul_f32_e32 v166, 0xbfb8aa3b, v119
	v_exp_f32_e32 v166, v166
	v_pk_mul_f32 v[126:127], v[128:129], v[126:127]
	v_add_f32_e32 v128, 1.0, v165
	v_mul_f32_e32 v165, 0xbfb8aa3b, v120
	v_add_f32_e32 v129, 1.0, v166
	v_exp_f32_e32 v165, v165
	v_mul_f32_e32 v166, 0xbfb8aa3b, v121
	v_exp_f32_e32 v167, v166
	v_rcp_f32_e32 v128, v128
	v_add_f32_e32 v165, 1.0, v165
	v_rcp_f32_e32 v129, v129
	v_rcp_f32_e32 v166, v165
	v_add_f32_e32 v165, 1.0, v167
	v_rcp_f32_e32 v167, v165
	v_pk_mul_f32 v[118:119], v[118:119], v[128:129]
	v_readlane_b32 s19, v254, 36
	v_pk_mul_f32 v[118:119], v[114:115], v[118:119]
	v_pk_mul_f32 v[114:115], v[120:121], v[166:167]
	v_cvt_pk_bf16_f32 v118, v118, v119
	v_pk_mul_f32 v[120:121], v[116:117], v[114:115]
	v_lshl_add_u32 v164, s58, 8, v160
	v_cvt_pk_bf16_f32 v119, v120, v121
	v_mul_f32_e32 v120, 0xbfb8aa3b, v110
	v_mul_f32_e32 v121, 0xbfb8aa3b, v111
	v_exp_f32_e32 v120, v120
	v_exp_f32_e32 v121, v121
	v_ashrrev_i32_e32 v139, 31, v138
	v_mov_b64_e32 v[158:159], s[18:19]
	v_mad_i64_i32 v[178:179], s[18:19], v164, s67, v[158:159]
	v_pk_mul_f32 v[124:125], v[124:125], v[126:127]
	v_lshlrev_b64 v[114:115], 1, v[138:139]
	v_lshl_add_u64 v[126:127], v[178:179], 0, v[114:115]
	v_cvt_pk_bf16_f32 v116, v122, v123
	v_cvt_pk_bf16_f32 v117, v124, v125
	flat_store_dwordx4 v[126:127], v[116:119]
	s_and_b64 vcc, exec, s[2:3]
	s_mov_b64 s[2:3], -1
	v_add_f32_e32 v116, 1.0, v120
	v_add_f32_e32 v117, 1.0, v121
	v_rcp_f32_e32 v116, v116
	v_rcp_f32_e32 v117, v117
	v_or_b32_e32 v118, 16, v164
	v_mad_i64_i32 v[118:119], s[18:19], v118, s67, v[158:159]
	v_pk_mul_f32 v[110:111], v[110:111], v[116:117]
	v_mul_f32_e32 v116, 0xbfb8aa3b, v112
	v_mul_f32_e32 v117, 0xbfb8aa3b, v113
	v_exp_f32_e32 v116, v116
	v_exp_f32_e32 v117, v117
	v_pk_mul_f32 v[106:107], v[106:107], v[110:111]
	v_add_f32_e32 v110, 1.0, v116
	v_add_f32_e32 v111, 1.0, v117
	v_mul_f32_e32 v116, 0xbfb8aa3b, v102
	v_mul_f32_e32 v117, 0xbfb8aa3b, v103
	v_rcp_f32_e32 v110, v110
	v_rcp_f32_e32 v111, v111
	v_exp_f32_e32 v116, v116
	v_exp_f32_e32 v117, v117
	v_pk_mul_f32 v[110:111], v[112:113], v[110:111]
	v_add_f32_e32 v112, 1.0, v116
	v_add_f32_e32 v113, 1.0, v117
	v_mul_f32_e32 v116, 0xbfb8aa3b, v104
	v_mul_f32_e32 v117, 0xbfb8aa3b, v105
	v_exp_f32_e32 v116, v116
	v_exp_f32_e32 v117, v117
	v_rcp_f32_e32 v112, v112
	v_rcp_f32_e32 v113, v113
	v_add_f32_e32 v116, 1.0, v116
	v_add_f32_e32 v117, 1.0, v117
	v_rcp_f32_e32 v116, v116
	v_rcp_f32_e32 v117, v117
	v_pk_mul_f32 v[102:103], v[102:103], v[112:113]
	v_pk_mul_f32 v[108:109], v[108:109], v[110:111]
	v_pk_mul_f32 v[102:103], v[98:99], v[102:103]
	v_pk_mul_f32 v[98:99], v[104:105], v[116:117]
	v_lshl_add_u64 v[110:111], v[118:119], 0, v[114:115]
	v_pk_mul_f32 v[104:105], v[100:101], v[98:99]
	v_cvt_pk_bf16_f32 v100, v102, v103
	v_mul_f32_e32 v102, 0xbfb8aa3b, v94
	v_mul_f32_e32 v103, 0xbfb8aa3b, v95
	v_exp_f32_e32 v102, v102
	v_exp_f32_e32 v103, v103
	v_cvt_pk_bf16_f32 v98, v106, v107
	v_cvt_pk_bf16_f32 v99, v108, v109
	v_cvt_pk_bf16_f32 v101, v104, v105
	flat_store_dwordx4 v[110:111], v[98:101]
	s_nop 1
	v_add_f32_e32 v98, 1.0, v102
	v_add_f32_e32 v99, 1.0, v103
	v_rcp_f32_e32 v98, v98
	v_rcp_f32_e32 v99, v99
	v_or_b32_e32 v100, 32, v164
	v_mad_i64_i32 v[100:101], s[18:19], v100, s67, v[158:159]
	v_pk_mul_f32 v[94:95], v[94:95], v[98:99]
	v_mul_f32_e32 v98, 0xbfb8aa3b, v96
	v_mul_f32_e32 v99, 0xbfb8aa3b, v97
	v_exp_f32_e32 v98, v98
	v_exp_f32_e32 v99, v99
	v_pk_mul_f32 v[90:91], v[90:91], v[94:95]
	v_add_f32_e32 v94, 1.0, v98
	v_add_f32_e32 v95, 1.0, v99
	v_mul_f32_e32 v98, 0xbfb8aa3b, v86
	v_mul_f32_e32 v99, 0xbfb8aa3b, v87
	v_rcp_f32_e32 v94, v94
	v_rcp_f32_e32 v95, v95
	v_exp_f32_e32 v98, v98
	v_exp_f32_e32 v99, v99
	v_pk_mul_f32 v[94:95], v[96:97], v[94:95]
	v_add_f32_e32 v96, 1.0, v98
	v_add_f32_e32 v97, 1.0, v99
	v_mul_f32_e32 v98, 0xbfb8aa3b, v88
	v_mul_f32_e32 v99, 0xbfb8aa3b, v89
	v_exp_f32_e32 v98, v98
	v_exp_f32_e32 v99, v99
	v_rcp_f32_e32 v96, v96
	v_rcp_f32_e32 v97, v97
	v_add_f32_e32 v98, 1.0, v98
	v_add_f32_e32 v99, 1.0, v99
	v_rcp_f32_e32 v98, v98
	v_rcp_f32_e32 v99, v99
	v_pk_mul_f32 v[86:87], v[86:87], v[96:97]
	v_pk_mul_f32 v[92:93], v[92:93], v[94:95]
	v_pk_mul_f32 v[86:87], v[82:83], v[86:87]
	v_pk_mul_f32 v[82:83], v[88:89], v[98:99]
	v_lshl_add_u64 v[94:95], v[100:101], 0, v[114:115]
	v_pk_mul_f32 v[88:89], v[84:85], v[82:83]
	v_cvt_pk_bf16_f32 v84, v86, v87
	v_mul_f32_e32 v86, 0xbfb8aa3b, v78
	v_mul_f32_e32 v87, 0xbfb8aa3b, v79
	v_exp_f32_e32 v86, v86
	v_exp_f32_e32 v87, v87
	v_cvt_pk_bf16_f32 v82, v90, v91
	v_cvt_pk_bf16_f32 v83, v92, v93
	v_cvt_pk_bf16_f32 v85, v88, v89
	flat_store_dwordx4 v[94:95], v[82:85]
	s_nop 1
	v_add_f32_e32 v82, 1.0, v86
	v_add_f32_e32 v83, 1.0, v87
	v_rcp_f32_e32 v82, v82
	v_rcp_f32_e32 v83, v83
	v_or_b32_e32 v84, 48, v164
	v_mad_i64_i32 v[84:85], s[18:19], v84, s67, v[158:159]
	v_pk_mul_f32 v[78:79], v[78:79], v[82:83]
	v_mul_f32_e32 v82, 0xbfb8aa3b, v80
	v_mul_f32_e32 v83, 0xbfb8aa3b, v81
; __device__ __forceinline__ float sigmoid_(float x) { return __builtin_amdgcn_rcpf(1.0f + __expf(-x)); }
; __device__ __forceinline__ uint4 pack8(const float (&f)[8]) { uint4 r; r.x = cvt_pk_bf16(f[0], f[1]); r.y = cvt_pk_bf16(f[2], f[3]); r.z = cvt_pk_bf16(f[4], f[5]); r.w = cvt_pk_bf16(f[6], f[7]); return r; }
; __device__ __forceinline__ void nt_store16(void* p, const uint4 v) { __builtin_nontemporal_store((u32x4){v.x, v.y, v.z, v.w}, (u32x4*)p); }
;     __device__ __forceinline__ void operator()(AccT acc, const Unit& u, int wr, int wc, int fr, int fq) const {
;     ...
;                 bf16_t* rowp = O + (size_t)(row0 + ai * HALF + m * 16) * FF_ + col0;
;                 float o[8];
; #pragma unroll
;                 for (int n = 0; n < 2; ++n)
; #pragma unroll
;                     for (int j = 0; j < 4; ++j) { const float gt = acc[ai][0][m][n][j], up = acc[ai][1][m][n][j]; o[n * 4 + j] = gt * sigmoid_(gt) * up; }
;                 nt_store16(rowp, pack8(o));
	v_exp_f32_e32 v82, v82
	v_exp_f32_e32 v83, v83
	v_pk_mul_f32 v[74:75], v[74:75], v[78:79]
	v_add_f32_e32 v78, 1.0, v82
	v_add_f32_e32 v79, 1.0, v83
	v_mul_f32_e32 v82, 0xbfb8aa3b, v70
	v_mul_f32_e32 v83, 0xbfb8aa3b, v71
	v_rcp_f32_e32 v78, v78
	v_rcp_f32_e32 v79, v79
	v_exp_f32_e32 v82, v82
	v_exp_f32_e32 v83, v83
	v_pk_mul_f32 v[78:79], v[80:81], v[78:79]
	v_add_f32_e32 v80, 1.0, v82
	v_add_f32_e32 v81, 1.0, v83
	v_mul_f32_e32 v82, 0xbfb8aa3b, v72
	v_mul_f32_e32 v83, 0xbfb8aa3b, v73
	v_exp_f32_e32 v82, v82
	v_exp_f32_e32 v83, v83
	v_rcp_f32_e32 v80, v80
	v_rcp_f32_e32 v81, v81
	v_add_f32_e32 v82, 1.0, v82
	v_add_f32_e32 v83, 1.0, v83
	v_rcp_f32_e32 v82, v82
	v_rcp_f32_e32 v83, v83
	v_pk_mul_f32 v[70:71], v[70:71], v[80:81]
	v_pk_mul_f32 v[76:77], v[76:77], v[78:79]
	v_pk_mul_f32 v[70:71], v[66:67], v[70:71]
	v_pk_mul_f32 v[66:67], v[72:73], v[82:83]
	v_lshl_add_u64 v[78:79], v[84:85], 0, v[114:115]
	v_pk_mul_f32 v[72:73], v[68:69], v[66:67]
	v_cvt_pk_bf16_f32 v68, v70, v71
	v_mul_f32_e32 v70, 0xbfb8aa3b, v62
	v_mul_f32_e32 v71, 0xbfb8aa3b, v63
	v_exp_f32_e32 v70, v70
	v_exp_f32_e32 v71, v71
	v_cvt_pk_bf16_f32 v66, v74, v75
	v_cvt_pk_bf16_f32 v67, v76, v77
	v_cvt_pk_bf16_f32 v69, v72, v73
	flat_store_dwordx4 v[78:79], v[66:69]
	s_nop 1
	v_add_f32_e32 v66, 1.0, v70
	v_add_f32_e32 v67, 1.0, v71
	v_rcp_f32_e32 v66, v66
	v_rcp_f32_e32 v67, v67
	v_add_u32_e32 v68, 0x80, v164
	v_mad_i64_i32 v[68:69], s[18:19], v68, s67, v[158:159]
	v_pk_mul_f32 v[62:63], v[62:63], v[66:67]
	v_mul_f32_e32 v66, 0xbfb8aa3b, v64
	v_mul_f32_e32 v67, 0xbfb8aa3b, v65
	v_exp_f32_e32 v66, v66
	v_exp_f32_e32 v67, v67
	v_pk_mul_f32 v[58:59], v[58:59], v[62:63]
	v_add_f32_e32 v62, 1.0, v66
	v_add_f32_e32 v63, 1.0, v67
	v_mul_f32_e32 v66, 0xbfb8aa3b, v54
	v_mul_f32_e32 v67, 0xbfb8aa3b, v55
	v_rcp_f32_e32 v62, v62
	v_rcp_f32_e32 v63, v63
	v_exp_f32_e32 v66, v66
	v_exp_f32_e32 v67, v67
	v_pk_mul_f32 v[62:63], v[64:65], v[62:63]
	v_add_f32_e32 v64, 1.0, v66
	v_add_f32_e32 v65, 1.0, v67
	v_mul_f32_e32 v66, 0xbfb8aa3b, v56
	v_mul_f32_e32 v67, 0xbfb8aa3b, v57
	v_exp_f32_e32 v66, v66
	v_exp_f32_e32 v67, v67
	v_rcp_f32_e32 v64, v64
	v_rcp_f32_e32 v65, v65
	v_add_f32_e32 v66, 1.0, v66
	v_add_f32_e32 v67, 1.0, v67
	v_rcp_f32_e32 v66, v66
	v_rcp_f32_e32 v67, v67
	v_pk_mul_f32 v[54:55], v[54:55], v[64:65]
	v_pk_mul_f32 v[60:61], v[60:61], v[62:63]
	v_pk_mul_f32 v[54:55], v[50:51], v[54:55]
	v_pk_mul_f32 v[50:51], v[56:57], v[66:67]
	v_lshl_add_u64 v[62:63], v[68:69], 0, v[114:115]
	v_pk_mul_f32 v[56:57], v[52:53], v[50:51]
	v_cvt_pk_bf16_f32 v52, v54, v55
	v_mul_f32_e32 v54, 0xbfb8aa3b, v46
	v_mul_f32_e32 v55, 0xbfb8aa3b, v47
	v_exp_f32_e32 v54, v54
	v_exp_f32_e32 v55, v55
	v_cvt_pk_bf16_f32 v50, v58, v59
	v_cvt_pk_bf16_f32 v51, v60, v61
	v_cvt_pk_bf16_f32 v53, v56, v57
	flat_store_dwordx4 v[62:63], v[50:53]
	s_nop 1
	v_add_f32_e32 v50, 1.0, v54
	v_add_f32_e32 v51, 1.0, v55
	v_rcp_f32_e32 v50, v50
	v_rcp_f32_e32 v51, v51
	v_add_u32_e32 v52, 0x90, v164
	v_mad_i64_i32 v[52:53], s[18:19], v52, s67, v[158:159]
	v_pk_mul_f32 v[46:47], v[46:47], v[50:51]
	v_mul_f32_e32 v50, 0xbfb8aa3b, v48
	v_mul_f32_e32 v51, 0xbfb8aa3b, v49
	v_exp_f32_e32 v50, v50
	v_exp_f32_e32 v51, v51
	v_pk_mul_f32 v[42:43], v[42:43], v[46:47]
	v_add_f32_e32 v46, 1.0, v50
	v_add_f32_e32 v47, 1.0, v51
	v_mul_f32_e32 v50, 0xbfb8aa3b, v38
	v_mul_f32_e32 v51, 0xbfb8aa3b, v39
	v_rcp_f32_e32 v46, v46
	v_rcp_f32_e32 v47, v47
	v_exp_f32_e32 v50, v50
	v_exp_f32_e32 v51, v51
	v_pk_mul_f32 v[46:47], v[48:49], v[46:47]
	v_add_f32_e32 v48, 1.0, v50
	v_add_f32_e32 v49, 1.0, v51
	v_mul_f32_e32 v50, 0xbfb8aa3b, v40
	v_mul_f32_e32 v51, 0xbfb8aa3b, v41
	v_exp_f32_e32 v50, v50
	v_exp_f32_e32 v51, v51
	v_rcp_f32_e32 v48, v48
	v_rcp_f32_e32 v49, v49
	v_add_f32_e32 v50, 1.0, v50
; __device__ __forceinline__ float sigmoid_(float x) { return __builtin_amdgcn_rcpf(1.0f + __expf(-x)); }
; __device__ __forceinline__ uint4 pack8(const float (&f)[8]) { uint4 r; r.x = cvt_pk_bf16(f[0], f[1]); r.y = cvt_pk_bf16(f[2], f[3]); r.z = cvt_pk_bf16(f[4], f[5]); r.w = cvt_pk_bf16(f[6], f[7]); return r; }
; __device__ __forceinline__ void nt_store16(void* p, const uint4 v) { __builtin_nontemporal_store((u32x4){v.x, v.y, v.z, v.w}, (u32x4*)p); }
;     __device__ __forceinline__ void operator()(AccT acc, const Unit& u, int wr, int wc, int fr, int fq) const {
;     ...
;                 bf16_t* rowp = O + (size_t)(row0 + ai * HALF + m * 16) * FF_ + col0;
;                 float o[8];
; #pragma unroll
;                 for (int n = 0; n < 2; ++n)
; #pragma unroll
;                     for (int j = 0; j < 4; ++j) { const float gt = acc[ai][0][m][n][j], up = acc[ai][1][m][n][j]; o[n * 4 + j] = gt * sigmoid_(gt) * up; }
;                 nt_store16(rowp, pack8(o));
	v_add_f32_e32 v51, 1.0, v51
	v_rcp_f32_e32 v50, v50
	v_rcp_f32_e32 v51, v51
	v_pk_mul_f32 v[38:39], v[38:39], v[48:49]
	v_pk_mul_f32 v[44:45], v[44:45], v[46:47]
	v_pk_mul_f32 v[38:39], v[34:35], v[38:39]
	v_pk_mul_f32 v[34:35], v[40:41], v[50:51]
	v_lshl_add_u64 v[46:47], v[52:53], 0, v[114:115]
	v_pk_mul_f32 v[40:41], v[36:37], v[34:35]
	v_cvt_pk_bf16_f32 v36, v38, v39
	v_mul_f32_e32 v38, 0xbfb8aa3b, v30
	v_mul_f32_e32 v39, 0xbfb8aa3b, v31
	v_exp_f32_e32 v38, v38
	v_exp_f32_e32 v39, v39
	v_cvt_pk_bf16_f32 v34, v42, v43
	v_cvt_pk_bf16_f32 v35, v44, v45
	v_cvt_pk_bf16_f32 v37, v40, v41
	flat_store_dwordx4 v[46:47], v[34:37]
	s_nop 1
	v_add_f32_e32 v34, 1.0, v38
	v_add_f32_e32 v35, 1.0, v39
	v_rcp_f32_e32 v34, v34
	v_rcp_f32_e32 v35, v35
	v_add_u32_e32 v36, 0xa0, v164
	v_mad_i64_i32 v[36:37], s[18:19], v36, s67, v[158:159]
	v_pk_mul_f32 v[30:31], v[30:31], v[34:35]
	v_mul_f32_e32 v34, 0xbfb8aa3b, v32
	v_mul_f32_e32 v35, 0xbfb8aa3b, v33
	v_exp_f32_e32 v34, v34
	v_exp_f32_e32 v35, v35
	v_pk_mul_f32 v[26:27], v[26:27], v[30:31]
	v_add_f32_e32 v30, 1.0, v34
	v_add_f32_e32 v31, 1.0, v35
	v_mul_f32_e32 v34, 0xbfb8aa3b, v22
	v_mul_f32_e32 v35, 0xbfb8aa3b, v23
	v_rcp_f32_e32 v30, v30
	v_rcp_f32_e32 v31, v31
	v_exp_f32_e32 v34, v34
	v_exp_f32_e32 v35, v35
	v_pk_mul_f32 v[30:31], v[32:33], v[30:31]
	v_add_f32_e32 v32, 1.0, v34
	v_add_f32_e32 v33, 1.0, v35
	v_mul_f32_e32 v34, 0xbfb8aa3b, v24
	v_mul_f32_e32 v35, 0xbfb8aa3b, v25
	v_exp_f32_e32 v34, v34
	v_exp_f32_e32 v35, v35
	v_rcp_f32_e32 v32, v32
	v_rcp_f32_e32 v33, v33
	v_add_f32_e32 v34, 1.0, v34
	v_add_f32_e32 v35, 1.0, v35
	v_rcp_f32_e32 v34, v34
	v_rcp_f32_e32 v35, v35
	v_pk_mul_f32 v[22:23], v[22:23], v[32:33]
	v_pk_mul_f32 v[28:29], v[28:29], v[30:31]
	v_pk_mul_f32 v[22:23], v[18:19], v[22:23]
	v_pk_mul_f32 v[18:19], v[24:25], v[34:35]
	v_lshl_add_u64 v[30:31], v[36:37], 0, v[114:115]
	v_pk_mul_f32 v[24:25], v[20:21], v[18:19]
	v_cvt_pk_bf16_f32 v20, v22, v23
	v_mul_f32_e32 v22, 0xbfb8aa3b, v14
	v_mul_f32_e32 v23, 0xbfb8aa3b, v15
	v_exp_f32_e32 v22, v22
	v_exp_f32_e32 v23, v23
	v_cvt_pk_bf16_f32 v18, v26, v27
	v_cvt_pk_bf16_f32 v19, v28, v29
	v_cvt_pk_bf16_f32 v21, v24, v25
	flat_store_dwordx4 v[30:31], v[18:21]
	s_nop 1
	v_add_f32_e32 v18, 1.0, v22
	v_add_f32_e32 v19, 1.0, v23
	v_rcp_f32_e32 v18, v18
	v_rcp_f32_e32 v19, v19
	v_add_u32_e32 v20, 0xb0, v164
	v_mad_i64_i32 v[20:21], s[18:19], v20, s67, v[158:159]
	v_pk_mul_f32 v[14:15], v[14:15], v[18:19]
	v_mul_f32_e32 v18, 0xbfb8aa3b, v16
	v_mul_f32_e32 v19, 0xbfb8aa3b, v17
	v_exp_f32_e32 v18, v18
	v_exp_f32_e32 v19, v19
	v_pk_mul_f32 v[10:11], v[10:11], v[14:15]
	v_add_f32_e32 v14, 1.0, v18
	v_add_f32_e32 v15, 1.0, v19
	v_mul_f32_e32 v18, 0xbfb8aa3b, v6
	v_mul_f32_e32 v19, 0xbfb8aa3b, v7
	v_rcp_f32_e32 v14, v14
	v_rcp_f32_e32 v15, v15
	v_exp_f32_e32 v18, v18
	v_exp_f32_e32 v19, v19
	v_pk_mul_f32 v[14:15], v[16:17], v[14:15]
	v_add_f32_e32 v16, 1.0, v18
	v_add_f32_e32 v17, 1.0, v19
	v_mul_f32_e32 v18, 0xbfb8aa3b, v8
	v_mul_f32_e32 v19, 0xbfb8aa3b, v9
	v_exp_f32_e32 v18, v18
	v_exp_f32_e32 v19, v19
	v_rcp_f32_e32 v16, v16
	v_rcp_f32_e32 v17, v17
	v_add_f32_e32 v18, 1.0, v18
	v_add_f32_e32 v19, 1.0, v19
	v_rcp_f32_e32 v18, v18
	v_rcp_f32_e32 v19, v19
	v_pk_mul_f32 v[6:7], v[6:7], v[16:17]
	v_pk_mul_f32 v[12:13], v[12:13], v[14:15]
	v_pk_mul_f32 v[6:7], v[2:3], v[6:7]
	v_pk_mul_f32 v[2:3], v[8:9], v[18:19]
	v_lshl_add_u64 v[14:15], v[20:21], 0, v[114:115]
	v_pk_mul_f32 v[8:9], v[4:5], v[2:3]
	v_cvt_pk_bf16_f32 v2, v10, v11
	v_cvt_pk_bf16_f32 v3, v12, v13
	v_cvt_pk_bf16_f32 v4, v6, v7
	v_cvt_pk_bf16_f32 v5, v8, v9
	flat_store_dwordx4 v[14:15], v[2:5]
	s_cbranch_vccnz .LBB0_60
	s_andn2_b64 vcc, exec, s[10:11]
	s_cbranch_vccnz .LBB0_59
	s_barrier
	s_branch .LBB0_59

; __device__ __forceinline__ float sigmoid_(float x) { return __builtin_amdgcn_rcpf(1.0f + __expf(-x)); }
; __device__ __forceinline__ uint4 pack8(const float (&f)[8]) { uint4 r; r.x = cvt_pk_bf16(f[0], f[1]); r.y = cvt_pk_bf16(f[2], f[3]); r.z = cvt_pk_bf16(f[4], f[5]); r.w = cvt_pk_bf16(f[6], f[7]); return r; }
; __device__ __forceinline__ void nt_store16(void* p, const uint4 v) { __builtin_nontemporal_store((u32x4){v.x, v.y, v.z, v.w}, (u32x4*)p); }
;     __device__ __forceinline__ void operator()(AccT acc, const Unit& u, int wr, int wc, int fr, int fq) const {
;     ...
;             for (int m = 0; m < 4; ++m) { const size_t row = (size_t)(row0 + ai * HALF + m * 16);
; #pragma unroll
;                 for (int bj = 0; bj < 2; ++bj) { float o[8];
; #pragma unroll
;                     for (int n = 0; n < 2; ++n)
; #pragma unroll
;                         for (int j = 0; j < 4; ++j) o[n * 4 + j] = sigmoid_(acc[ai][bj][m][n][j]);
;                     nt_store16(G + row * 3072 + col0 + bj * HALF, pack8(o)); } }
.LBB0_180:
	v_mul_f32_e32 v126, 0xbfb8aa3b, v126
	v_mul_f32_e32 v122, 0xbfb8aa3b, v122
	v_exp_f32_e32 v126, v126
	v_mul_f32_e32 v127, 0xbfb8aa3b, v127
	v_exp_f32_e32 v122, v122
	v_mul_f32_e32 v123, 0xbfb8aa3b, v123
	v_exp_f32_e32 v127, v127
	v_exp_f32_e32 v123, v123
	v_add_f32_e32 v126, 1.0, v126
	v_add_f32_e32 v122, 1.0, v122
	v_rcp_f32_e32 v163, v126
	v_add_f32_e32 v126, 1.0, v127
	v_mul_f32_e32 v127, 0xbfb8aa3b, v128
	v_rcp_f32_e32 v165, v122
	v_add_f32_e32 v122, 1.0, v123
	v_mul_f32_e32 v123, 0xbfb8aa3b, v124
	v_exp_f32_e32 v127, v127
	v_mul_f32_e32 v128, 0xbfb8aa3b, v129
	v_exp_f32_e32 v123, v123
	v_mul_f32_e32 v124, 0xbfb8aa3b, v125
	v_exp_f32_e32 v128, v128
	v_exp_f32_e32 v124, v124
	v_rcp_f32_e32 v129, v126
	v_add_f32_e32 v126, 1.0, v127
	v_rcp_f32_e32 v166, v122
	v_add_f32_e32 v122, 1.0, v123
	v_rcp_f32_e32 v164, v126
	v_add_f32_e32 v126, 1.0, v128
	v_rcp_f32_e32 v167, v122
	v_add_f32_e32 v122, 1.0, v124
	v_mul_f32_e32 v114, 0xbfb8aa3b, v114
	v_rcp_f32_e32 v128, v126
	v_rcp_f32_e32 v178, v122
	v_readlane_b32 s18, v254, 35
	v_exp_f32_e32 v114, v114
	v_mul_f32_e32 v115, 0xbfb8aa3b, v115
	v_lshl_or_b32 v138, s59, 8, v160
	v_readlane_b32 s19, v254, 36
	v_exp_f32_e32 v115, v115
	v_lshl_add_u32 v162, s58, 8, v158
	v_ashrrev_i32_e32 v139, 31, v138
	v_mov_b64_e32 v[122:123], s[18:19]
	s_movk_i32 s20, 0x1800
	v_mad_i64_i32 v[126:127], s[18:19], v162, s20, v[122:123]
	v_lshlrev_b64 v[124:125], 1, v[138:139]
	v_lshl_add_u64 v[138:139], v[126:127], 0, v[124:125]
	v_cvt_pk_bf16_f32 v126, v163, v129
	v_cvt_pk_bf16_f32 v127, v164, v128
	v_cvt_pk_bf16_f32 v128, v165, v166
	v_cvt_pk_bf16_f32 v129, v167, v178
	v_add_f32_e32 v114, 1.0, v114
	flat_store_dwordx4 v[138:139], v[126:129]
	v_mul_f32_e32 v118, 0xbfb8aa3b, v118
	v_mul_f32_e32 v119, 0xbfb8aa3b, v119
	v_rcp_f32_e32 v126, v114
	v_add_f32_e32 v114, 1.0, v115
	v_mul_f32_e32 v115, 0xbfb8aa3b, v116
	v_mul_f32_e32 v120, 0xbfb8aa3b, v120
	v_mul_f32_e32 v121, 0xbfb8aa3b, v121
	v_exp_f32_e32 v115, v115
	v_mul_f32_e32 v116, 0xbfb8aa3b, v117
	v_exp_f32_e32 v118, v118
	v_exp_f32_e32 v119, v119
	v_exp_f32_e32 v120, v120
	v_exp_f32_e32 v121, v121
	v_exp_f32_e32 v116, v116
	v_rcp_f32_e32 v117, v114
	v_add_f32_e32 v114, 1.0, v115
	v_add_f32_e32 v118, 1.0, v118
	v_add_f32_e32 v119, 1.0, v119
	v_add_f32_e32 v120, 1.0, v120
	v_add_f32_e32 v121, 1.0, v121
	v_rcp_f32_e32 v127, v114
	v_add_f32_e32 v114, 1.0, v116
	v_mul_f32_e32 v110, 0xbfb8aa3b, v110
	v_mul_f32_e32 v106, 0xbfb8aa3b, v106
	v_rcp_f32_e32 v118, v118
	v_rcp_f32_e32 v119, v119
	v_rcp_f32_e32 v120, v120
	v_rcp_f32_e32 v121, v121
	v_rcp_f32_e32 v128, v114
	v_exp_f32_e32 v110, v110
	v_mul_f32_e32 v111, 0xbfb8aa3b, v111
	v_exp_f32_e32 v106, v106
	v_mul_f32_e32 v107, 0xbfb8aa3b, v107
	v_exp_f32_e32 v111, v111
	v_exp_f32_e32 v107, v107
	v_cvt_pk_bf16_f32 v114, v118, v119
	v_cvt_pk_bf16_f32 v115, v120, v121
	v_cvt_pk_bf16_f32 v116, v126, v117
	v_cvt_pk_bf16_f32 v117, v127, v128
	v_add_f32_e32 v110, 1.0, v110
	v_add_f32_e32 v106, 1.0, v106
	flat_store_dwordx4 v[138:139], v[114:117] offset:256
	v_mul_f32_e32 v98, 0xbfb8aa3b, v98
	v_exp_f32_e32 v98, v98
	v_rcp_f32_e32 v115, v110
	v_add_f32_e32 v110, 1.0, v111
	v_mul_f32_e32 v111, 0xbfb8aa3b, v112
	v_rcp_f32_e32 v117, v106
	v_add_f32_e32 v106, 1.0, v107
	v_mul_f32_e32 v107, 0xbfb8aa3b, v108
	v_exp_f32_e32 v111, v111
	v_mul_f32_e32 v112, 0xbfb8aa3b, v113
	v_exp_f32_e32 v107, v107
	v_mul_f32_e32 v108, 0xbfb8aa3b, v109
	v_exp_f32_e32 v112, v112
	v_exp_f32_e32 v108, v108
	v_rcp_f32_e32 v113, v110
	v_add_f32_e32 v110, 1.0, v111
	v_rcp_f32_e32 v109, v106
	v_add_f32_e32 v106, 1.0, v107
	v_rcp_f32_e32 v116, v110
	v_add_f32_e32 v110, 1.0, v112
	v_rcp_f32_e32 v118, v106
	v_add_f32_e32 v106, 1.0, v108
	v_rcp_f32_e32 v112, v110
	v_rcp_f32_e32 v119, v106
	v_mul_f32_e32 v99, 0xbfb8aa3b, v99
	v_exp_f32_e32 v99, v99
	v_or_b32_e32 v114, 16, v162
	v_mad_i64_i32 v[106:107], s[18:19], v114, s20, v[122:123]
	v_lshl_add_u64 v[110:111], v[106:107], 0, v[124:125]
	v_cvt_pk_bf16_f32 v106, v115, v113
	v_cvt_pk_bf16_f32 v107, v116, v112
	v_cvt_pk_bf16_f32 v108, v117, v109
	v_cvt_pk_bf16_f32 v109, v118, v119
	v_add_f32_e32 v98, 1.0, v98
	flat_store_dwordx4 v[110:111], v[106:109]
	v_mul_f32_e32 v102, 0xbfb8aa3b, v102
	v_mul_f32_e32 v103, 0xbfb8aa3b, v103
	v_rcp_f32_e32 v106, v98
	v_add_f32_e32 v98, 1.0, v99
	v_mul_f32_e32 v99, 0xbfb8aa3b, v100
	v_mul_f32_e32 v104, 0xbfb8aa3b, v104
	v_mul_f32_e32 v105, 0xbfb8aa3b, v105
	v_exp_f32_e32 v99, v99
	v_mul_f32_e32 v100, 0xbfb8aa3b, v101
	v_exp_f32_e32 v102, v102
	v_exp_f32_e32 v103, v103
	v_exp_f32_e32 v104, v104
	v_exp_f32_e32 v105, v105
	v_exp_f32_e32 v100, v100
	v_rcp_f32_e32 v101, v98
	v_add_f32_e32 v98, 1.0, v99
	v_add_f32_e32 v102, 1.0, v102
	v_add_f32_e32 v103, 1.0, v103
	v_add_f32_e32 v104, 1.0, v104
	v_add_f32_e32 v105, 1.0, v105
	v_rcp_f32_e32 v107, v98
	v_add_f32_e32 v98, 1.0, v100
	v_mul_f32_e32 v94, 0xbfb8aa3b, v94
	v_mul_f32_e32 v90, 0xbfb8aa3b, v90
	v_rcp_f32_e32 v102, v102
	v_rcp_f32_e32 v103, v103
	v_rcp_f32_e32 v104, v104
	v_rcp_f32_e32 v105, v105
	v_rcp_f32_e32 v108, v98
	v_exp_f32_e32 v94, v94
	v_mul_f32_e32 v95, 0xbfb8aa3b, v95
	v_exp_f32_e32 v90, v90
	v_mul_f32_e32 v91, 0xbfb8aa3b, v91
	v_exp_f32_e32 v95, v95
	v_exp_f32_e32 v91, v91
	v_cvt_pk_bf16_f32 v98, v102, v103
	v_cvt_pk_bf16_f32 v99, v104, v105
	v_cvt_pk_bf16_f32 v100, v106, v101
	v_cvt_pk_bf16_f32 v101, v107, v108
	v_add_f32_e32 v94, 1.0, v94
	v_add_f32_e32 v90, 1.0, v90
	flat_store_dwordx4 v[110:111], v[98:101] offset:256
	v_mul_f32_e32 v82, 0xbfb8aa3b, v82
	v_exp_f32_e32 v82, v82
	v_rcp_f32_e32 v99, v94
	v_add_f32_e32 v94, 1.0, v95
	v_mul_f32_e32 v95, 0xbfb8aa3b, v96
	v_rcp_f32_e32 v101, v90
	v_add_f32_e32 v90, 1.0, v91
; __device__ __forceinline__ float sigmoid_(float x) { return __builtin_amdgcn_rcpf(1.0f + __expf(-x)); }
; __device__ __forceinline__ uint4 pack8(const float (&f)[8]) { uint4 r; r.x = cvt_pk_bf16(f[0], f[1]); r.y = cvt_pk_bf16(f[2], f[3]); r.z = cvt_pk_bf16(f[4], f[5]); r.w = cvt_pk_bf16(f[6], f[7]); return r; }
; __device__ __forceinline__ void nt_store16(void* p, const uint4 v) { __builtin_nontemporal_store((u32x4){v.x, v.y, v.z, v.w}, (u32x4*)p); }
;     __device__ __forceinline__ void operator()(AccT acc, const Unit& u, int wr, int wc, int fr, int fq) const {
;     ...
;             for (int m = 0; m < 4; ++m) { const size_t row = (size_t)(row0 + ai * HALF + m * 16);
; #pragma unroll
;                 for (int bj = 0; bj < 2; ++bj) { float o[8];
; #pragma unroll
;                     for (int n = 0; n < 2; ++n)
; #pragma unroll
;                         for (int j = 0; j < 4; ++j) o[n * 4 + j] = sigmoid_(acc[ai][bj][m][n][j]);
;                     nt_store16(G + row * 3072 + col0 + bj * HALF, pack8(o)); } }
	v_mul_f32_e32 v91, 0xbfb8aa3b, v92
	v_exp_f32_e32 v95, v95
	v_mul_f32_e32 v96, 0xbfb8aa3b, v97
	v_exp_f32_e32 v91, v91
	v_mul_f32_e32 v92, 0xbfb8aa3b, v93
	v_exp_f32_e32 v96, v96
	v_exp_f32_e32 v92, v92
	v_rcp_f32_e32 v97, v94
	v_add_f32_e32 v94, 1.0, v95
	v_rcp_f32_e32 v93, v90
	v_add_f32_e32 v90, 1.0, v91
	v_rcp_f32_e32 v100, v94
	v_add_f32_e32 v94, 1.0, v96
	v_rcp_f32_e32 v102, v90
	v_add_f32_e32 v90, 1.0, v92
	v_rcp_f32_e32 v96, v94
	v_rcp_f32_e32 v103, v90
	v_mul_f32_e32 v83, 0xbfb8aa3b, v83
	v_exp_f32_e32 v83, v83
	v_or_b32_e32 v98, 32, v162
	v_mad_i64_i32 v[90:91], s[18:19], v98, s20, v[122:123]
	v_lshl_add_u64 v[94:95], v[90:91], 0, v[124:125]
	v_cvt_pk_bf16_f32 v90, v99, v97
	v_cvt_pk_bf16_f32 v91, v100, v96
	v_cvt_pk_bf16_f32 v92, v101, v93
	v_cvt_pk_bf16_f32 v93, v102, v103
	v_add_f32_e32 v82, 1.0, v82
	flat_store_dwordx4 v[94:95], v[90:93]
	v_mul_f32_e32 v86, 0xbfb8aa3b, v86
	v_mul_f32_e32 v87, 0xbfb8aa3b, v87
	v_rcp_f32_e32 v90, v82
	v_add_f32_e32 v82, 1.0, v83
	v_mul_f32_e32 v83, 0xbfb8aa3b, v84
	v_mul_f32_e32 v88, 0xbfb8aa3b, v88
	v_mul_f32_e32 v89, 0xbfb8aa3b, v89
	v_exp_f32_e32 v83, v83
	v_mul_f32_e32 v84, 0xbfb8aa3b, v85
	v_exp_f32_e32 v86, v86
	v_exp_f32_e32 v87, v87
	v_exp_f32_e32 v88, v88
	v_exp_f32_e32 v89, v89
	v_exp_f32_e32 v84, v84
	v_rcp_f32_e32 v85, v82
	v_add_f32_e32 v82, 1.0, v83
	v_add_f32_e32 v86, 1.0, v86
	v_add_f32_e32 v87, 1.0, v87
	v_add_f32_e32 v88, 1.0, v88
	v_add_f32_e32 v89, 1.0, v89
	v_rcp_f32_e32 v91, v82
	v_add_f32_e32 v82, 1.0, v84
	v_mul_f32_e32 v78, 0xbfb8aa3b, v78
	v_mul_f32_e32 v74, 0xbfb8aa3b, v74
	v_rcp_f32_e32 v86, v86
	v_rcp_f32_e32 v87, v87
	v_rcp_f32_e32 v88, v88
	v_rcp_f32_e32 v89, v89
	v_rcp_f32_e32 v92, v82
	v_exp_f32_e32 v78, v78
	v_mul_f32_e32 v79, 0xbfb8aa3b, v79
	v_exp_f32_e32 v74, v74
	v_mul_f32_e32 v75, 0xbfb8aa3b, v75
	v_exp_f32_e32 v79, v79
	v_exp_f32_e32 v75, v75
	v_cvt_pk_bf16_f32 v82, v86, v87
	v_cvt_pk_bf16_f32 v83, v88, v89
	v_cvt_pk_bf16_f32 v84, v90, v85
	v_cvt_pk_bf16_f32 v85, v91, v92
	v_add_f32_e32 v78, 1.0, v78
	v_add_f32_e32 v74, 1.0, v74
	flat_store_dwordx4 v[94:95], v[82:85] offset:256
	v_mul_f32_e32 v66, 0xbfb8aa3b, v66
	v_exp_f32_e32 v66, v66
	v_rcp_f32_e32 v83, v78
	v_add_f32_e32 v78, 1.0, v79
	v_mul_f32_e32 v79, 0xbfb8aa3b, v80
	v_rcp_f32_e32 v85, v74
	v_add_f32_e32 v74, 1.0, v75
	v_mul_f32_e32 v75, 0xbfb8aa3b, v76
	v_exp_f32_e32 v79, v79
	v_mul_f32_e32 v80, 0xbfb8aa3b, v81
	v_exp_f32_e32 v75, v75
	v_mul_f32_e32 v76, 0xbfb8aa3b, v77
	v_exp_f32_e32 v80, v80
	v_exp_f32_e32 v76, v76
	v_rcp_f32_e32 v81, v78
	v_add_f32_e32 v78, 1.0, v79
	v_rcp_f32_e32 v77, v74
	v_add_f32_e32 v74, 1.0, v75
	v_rcp_f32_e32 v84, v78
	v_add_f32_e32 v78, 1.0, v80
	v_rcp_f32_e32 v86, v74
	v_add_f32_e32 v74, 1.0, v76
	v_rcp_f32_e32 v80, v78
	v_rcp_f32_e32 v87, v74
	v_mul_f32_e32 v67, 0xbfb8aa3b, v67
	v_exp_f32_e32 v67, v67
	v_or_b32_e32 v82, 48, v162
	v_mad_i64_i32 v[74:75], s[18:19], v82, s20, v[122:123]
	v_lshl_add_u64 v[78:79], v[74:75], 0, v[124:125]
	v_cvt_pk_bf16_f32 v74, v83, v81
	v_cvt_pk_bf16_f32 v75, v84, v80
	v_cvt_pk_bf16_f32 v76, v85, v77
	v_cvt_pk_bf16_f32 v77, v86, v87
	v_add_f32_e32 v66, 1.0, v66
	flat_store_dwordx4 v[78:79], v[74:77]
	v_mul_f32_e32 v70, 0xbfb8aa3b, v70
	v_mul_f32_e32 v71, 0xbfb8aa3b, v71
	v_rcp_f32_e32 v74, v66
	v_add_f32_e32 v66, 1.0, v67
	v_mul_f32_e32 v67, 0xbfb8aa3b, v68
	v_mul_f32_e32 v72, 0xbfb8aa3b, v72
	v_mul_f32_e32 v73, 0xbfb8aa3b, v73
	v_exp_f32_e32 v67, v67
	v_mul_f32_e32 v68, 0xbfb8aa3b, v69
	v_exp_f32_e32 v70, v70
	v_exp_f32_e32 v71, v71
	v_exp_f32_e32 v72, v72
	v_exp_f32_e32 v73, v73
	v_exp_f32_e32 v68, v68
	v_rcp_f32_e32 v69, v66
	v_add_f32_e32 v66, 1.0, v67
	v_add_f32_e32 v70, 1.0, v70
	v_add_f32_e32 v71, 1.0, v71
	v_add_f32_e32 v72, 1.0, v72
	v_add_f32_e32 v73, 1.0, v73
	v_rcp_f32_e32 v75, v66
	v_add_f32_e32 v66, 1.0, v68
	v_mul_f32_e32 v62, 0xbfb8aa3b, v62
	v_mul_f32_e32 v58, 0xbfb8aa3b, v58
	v_rcp_f32_e32 v70, v70
	v_rcp_f32_e32 v71, v71
	v_rcp_f32_e32 v72, v72
	v_rcp_f32_e32 v73, v73
	v_rcp_f32_e32 v76, v66
	v_exp_f32_e32 v62, v62
	v_mul_f32_e32 v63, 0xbfb8aa3b, v63
	v_exp_f32_e32 v58, v58
	v_mul_f32_e32 v59, 0xbfb8aa3b, v59
	v_exp_f32_e32 v63, v63
	v_exp_f32_e32 v59, v59
	v_cvt_pk_bf16_f32 v66, v70, v71
	v_cvt_pk_bf16_f32 v67, v72, v73
	v_cvt_pk_bf16_f32 v68, v74, v69
	v_cvt_pk_bf16_f32 v69, v75, v76
	v_add_f32_e32 v62, 1.0, v62
	v_add_f32_e32 v58, 1.0, v58
	flat_store_dwordx4 v[78:79], v[66:69] offset:256
	v_mul_f32_e32 v50, 0xbfb8aa3b, v50
	v_exp_f32_e32 v50, v50
	v_rcp_f32_e32 v67, v62
	v_add_f32_e32 v62, 1.0, v63
	v_mul_f32_e32 v63, 0xbfb8aa3b, v64
	v_rcp_f32_e32 v69, v58
	v_add_f32_e32 v58, 1.0, v59
	v_mul_f32_e32 v59, 0xbfb8aa3b, v60
	v_exp_f32_e32 v63, v63
	v_mul_f32_e32 v64, 0xbfb8aa3b, v65
	v_exp_f32_e32 v59, v59
	v_mul_f32_e32 v60, 0xbfb8aa3b, v61
	v_exp_f32_e32 v64, v64
	v_exp_f32_e32 v60, v60
	v_rcp_f32_e32 v65, v62
	v_add_f32_e32 v62, 1.0, v63
	v_rcp_f32_e32 v61, v58
	v_add_f32_e32 v58, 1.0, v59
	v_rcp_f32_e32 v68, v62
	v_add_f32_e32 v62, 1.0, v64
	v_rcp_f32_e32 v70, v58
	v_add_f32_e32 v58, 1.0, v60
	v_rcp_f32_e32 v64, v62
	v_rcp_f32_e32 v71, v58
	v_mul_f32_e32 v51, 0xbfb8aa3b, v51
	v_exp_f32_e32 v51, v51
	v_add_u32_e32 v66, 0x80, v162
	v_mad_i64_i32 v[58:59], s[18:19], v66, s20, v[122:123]
	v_lshl_add_u64 v[62:63], v[58:59], 0, v[124:125]
	v_cvt_pk_bf16_f32 v58, v67, v65
	v_cvt_pk_bf16_f32 v59, v68, v64
	v_cvt_pk_bf16_f32 v60, v69, v61
	v_cvt_pk_bf16_f32 v61, v70, v71
	v_add_f32_e32 v50, 1.0, v50
	flat_store_dwordx4 v[62:63], v[58:61]
	v_mul_f32_e32 v54, 0xbfb8aa3b, v54
	v_mul_f32_e32 v55, 0xbfb8aa3b, v55
	v_rcp_f32_e32 v58, v50
	v_add_f32_e32 v50, 1.0, v51
	v_mul_f32_e32 v51, 0xbfb8aa3b, v52
	v_mul_f32_e32 v56, 0xbfb8aa3b, v56
; __device__ __forceinline__ float sigmoid_(float x) { return __builtin_amdgcn_rcpf(1.0f + __expf(-x)); }
; __device__ __forceinline__ uint4 pack8(const float (&f)[8]) { uint4 r; r.x = cvt_pk_bf16(f[0], f[1]); r.y = cvt_pk_bf16(f[2], f[3]); r.z = cvt_pk_bf16(f[4], f[5]); r.w = cvt_pk_bf16(f[6], f[7]); return r; }
; __device__ __forceinline__ void nt_store16(void* p, const uint4 v) { __builtin_nontemporal_store((u32x4){v.x, v.y, v.z, v.w}, (u32x4*)p); }
;     __device__ __forceinline__ void operator()(AccT acc, const Unit& u, int wr, int wc, int fr, int fq) const {
;     ...
;             for (int m = 0; m < 4; ++m) { const size_t row = (size_t)(row0 + ai * HALF + m * 16);
; #pragma unroll
;                 for (int bj = 0; bj < 2; ++bj) { float o[8];
; #pragma unroll
;                     for (int n = 0; n < 2; ++n)
; #pragma unroll
;                         for (int j = 0; j < 4; ++j) o[n * 4 + j] = sigmoid_(acc[ai][bj][m][n][j]);
;                     nt_store16(G + row * 3072 + col0 + bj * HALF, pack8(o)); } }
	v_mul_f32_e32 v57, 0xbfb8aa3b, v57
	v_exp_f32_e32 v51, v51
	v_mul_f32_e32 v52, 0xbfb8aa3b, v53
	v_exp_f32_e32 v54, v54
	v_exp_f32_e32 v55, v55
	v_exp_f32_e32 v56, v56
	v_exp_f32_e32 v57, v57
	v_exp_f32_e32 v52, v52
	v_rcp_f32_e32 v53, v50
	v_add_f32_e32 v50, 1.0, v51
	v_add_f32_e32 v54, 1.0, v54
	v_add_f32_e32 v55, 1.0, v55
	v_add_f32_e32 v56, 1.0, v56
	v_add_f32_e32 v57, 1.0, v57
	v_rcp_f32_e32 v59, v50
	v_add_f32_e32 v50, 1.0, v52
	v_mul_f32_e32 v46, 0xbfb8aa3b, v46
	v_mul_f32_e32 v42, 0xbfb8aa3b, v42
	v_rcp_f32_e32 v54, v54
	v_rcp_f32_e32 v55, v55
	v_rcp_f32_e32 v56, v56
	v_rcp_f32_e32 v57, v57
	v_rcp_f32_e32 v60, v50
	v_exp_f32_e32 v46, v46
	v_mul_f32_e32 v47, 0xbfb8aa3b, v47
	v_exp_f32_e32 v42, v42
	v_mul_f32_e32 v43, 0xbfb8aa3b, v43
	v_exp_f32_e32 v47, v47
	v_exp_f32_e32 v43, v43
	v_cvt_pk_bf16_f32 v50, v54, v55
	v_cvt_pk_bf16_f32 v51, v56, v57
	v_cvt_pk_bf16_f32 v52, v58, v53
	v_cvt_pk_bf16_f32 v53, v59, v60
	v_add_f32_e32 v46, 1.0, v46
	v_add_f32_e32 v42, 1.0, v42
	flat_store_dwordx4 v[62:63], v[50:53] offset:256
	v_mul_f32_e32 v34, 0xbfb8aa3b, v34
	v_exp_f32_e32 v34, v34
	v_rcp_f32_e32 v51, v46
	v_add_f32_e32 v46, 1.0, v47
	v_mul_f32_e32 v47, 0xbfb8aa3b, v48
	v_rcp_f32_e32 v53, v42
	v_add_f32_e32 v42, 1.0, v43
	v_mul_f32_e32 v43, 0xbfb8aa3b, v44
	v_exp_f32_e32 v47, v47
	v_mul_f32_e32 v48, 0xbfb8aa3b, v49
	v_exp_f32_e32 v43, v43
	v_mul_f32_e32 v44, 0xbfb8aa3b, v45
	v_exp_f32_e32 v48, v48
	v_exp_f32_e32 v44, v44
	v_rcp_f32_e32 v49, v46
	v_add_f32_e32 v46, 1.0, v47
	v_rcp_f32_e32 v45, v42
	v_add_f32_e32 v42, 1.0, v43
	v_rcp_f32_e32 v52, v46
	v_add_f32_e32 v46, 1.0, v48
	v_rcp_f32_e32 v54, v42
	v_add_f32_e32 v42, 1.0, v44
	v_rcp_f32_e32 v48, v46
	v_rcp_f32_e32 v55, v42
	v_mul_f32_e32 v35, 0xbfb8aa3b, v35
	v_exp_f32_e32 v35, v35
	v_add_u32_e32 v50, 0x90, v162
	v_mad_i64_i32 v[42:43], s[18:19], v50, s20, v[122:123]
	v_lshl_add_u64 v[46:47], v[42:43], 0, v[124:125]
	v_cvt_pk_bf16_f32 v42, v51, v49
	v_cvt_pk_bf16_f32 v43, v52, v48
	v_cvt_pk_bf16_f32 v44, v53, v45
	v_cvt_pk_bf16_f32 v45, v54, v55
	v_add_f32_e32 v34, 1.0, v34
	flat_store_dwordx4 v[46:47], v[42:45]
	v_mul_f32_e32 v38, 0xbfb8aa3b, v38
	v_mul_f32_e32 v39, 0xbfb8aa3b, v39
	v_rcp_f32_e32 v42, v34
	v_add_f32_e32 v34, 1.0, v35
	v_mul_f32_e32 v35, 0xbfb8aa3b, v36
	v_mul_f32_e32 v40, 0xbfb8aa3b, v40
	v_mul_f32_e32 v41, 0xbfb8aa3b, v41
	v_exp_f32_e32 v35, v35
	v_mul_f32_e32 v36, 0xbfb8aa3b, v37
	v_exp_f32_e32 v38, v38
	v_exp_f32_e32 v39, v39
	v_exp_f32_e32 v40, v40
	v_exp_f32_e32 v41, v41
	v_exp_f32_e32 v36, v36
	v_rcp_f32_e32 v37, v34
	v_add_f32_e32 v34, 1.0, v35
	v_add_f32_e32 v38, 1.0, v38
	v_add_f32_e32 v39, 1.0, v39
	v_add_f32_e32 v40, 1.0, v40
	v_add_f32_e32 v41, 1.0, v41
	v_rcp_f32_e32 v43, v34
	v_add_f32_e32 v34, 1.0, v36
	v_mul_f32_e32 v30, 0xbfb8aa3b, v30
	v_mul_f32_e32 v26, 0xbfb8aa3b, v26
	v_rcp_f32_e32 v38, v38
	v_rcp_f32_e32 v39, v39
	v_rcp_f32_e32 v40, v40
	v_rcp_f32_e32 v41, v41
	v_rcp_f32_e32 v44, v34
	v_exp_f32_e32 v30, v30
	v_mul_f32_e32 v31, 0xbfb8aa3b, v31
	v_exp_f32_e32 v26, v26
	v_mul_f32_e32 v27, 0xbfb8aa3b, v27
	v_exp_f32_e32 v31, v31
	v_exp_f32_e32 v27, v27
	v_cvt_pk_bf16_f32 v34, v38, v39
	v_cvt_pk_bf16_f32 v35, v40, v41
	v_cvt_pk_bf16_f32 v36, v42, v37
	v_cvt_pk_bf16_f32 v37, v43, v44
	v_add_f32_e32 v30, 1.0, v30
	v_add_f32_e32 v26, 1.0, v26
	flat_store_dwordx4 v[46:47], v[34:37] offset:256
	v_mul_f32_e32 v18, 0xbfb8aa3b, v18
	v_exp_f32_e32 v18, v18
	v_rcp_f32_e32 v35, v30
	v_add_f32_e32 v30, 1.0, v31
	v_mul_f32_e32 v31, 0xbfb8aa3b, v32
	v_rcp_f32_e32 v37, v26
	v_add_f32_e32 v26, 1.0, v27
	v_mul_f32_e32 v27, 0xbfb8aa3b, v28
	v_exp_f32_e32 v31, v31
	v_mul_f32_e32 v32, 0xbfb8aa3b, v33
	v_exp_f32_e32 v27, v27
	v_mul_f32_e32 v28, 0xbfb8aa3b, v29
	v_exp_f32_e32 v32, v32
	v_exp_f32_e32 v28, v28
	v_rcp_f32_e32 v33, v30
	v_add_f32_e32 v30, 1.0, v31
	v_rcp_f32_e32 v29, v26
	v_add_f32_e32 v26, 1.0, v27
	v_rcp_f32_e32 v36, v30
; __device__ __forceinline__ float sigmoid_(float x) { return __builtin_amdgcn_rcpf(1.0f + __expf(-x)); }
; __device__ __forceinline__ uint4 pack8(const float (&f)[8]) { uint4 r; r.x = cvt_pk_bf16(f[0], f[1]); r.y = cvt_pk_bf16(f[2], f[3]); r.z = cvt_pk_bf16(f[4], f[5]); r.w = cvt_pk_bf16(f[6], f[7]); return r; }
; __device__ __forceinline__ void nt_store16(void* p, const uint4 v) { __builtin_nontemporal_store((u32x4){v.x, v.y, v.z, v.w}, (u32x4*)p); }
;     __device__ __forceinline__ void operator()(AccT acc, const Unit& u, int wr, int wc, int fr, int fq) const {
;     ...
;             for (int m = 0; m < 4; ++m) { const size_t row = (size_t)(row0 + ai * HALF + m * 16);
; #pragma unroll
;                 for (int bj = 0; bj < 2; ++bj) { float o[8];
; #pragma unroll
;                     for (int n = 0; n < 2; ++n)
; #pragma unroll
;                         for (int j = 0; j < 4; ++j) o[n * 4 + j] = sigmoid_(acc[ai][bj][m][n][j]);
;                     nt_store16(G + row * 3072 + col0 + bj * HALF, pack8(o)); } }
	v_add_f32_e32 v30, 1.0, v32
	v_rcp_f32_e32 v38, v26
	v_add_f32_e32 v26, 1.0, v28
	v_rcp_f32_e32 v32, v30
	v_rcp_f32_e32 v39, v26
	v_mul_f32_e32 v19, 0xbfb8aa3b, v19
	v_exp_f32_e32 v19, v19
	v_add_u32_e32 v34, 0xa0, v162
	v_mad_i64_i32 v[26:27], s[18:19], v34, s20, v[122:123]
	v_lshl_add_u64 v[30:31], v[26:27], 0, v[124:125]
	v_cvt_pk_bf16_f32 v26, v35, v33
	v_cvt_pk_bf16_f32 v27, v36, v32
	v_cvt_pk_bf16_f32 v28, v37, v29
	v_cvt_pk_bf16_f32 v29, v38, v39
	v_add_f32_e32 v18, 1.0, v18
	flat_store_dwordx4 v[30:31], v[26:29]
	v_mul_f32_e32 v22, 0xbfb8aa3b, v22
	v_mul_f32_e32 v23, 0xbfb8aa3b, v23
	v_rcp_f32_e32 v26, v18
	v_add_f32_e32 v18, 1.0, v19
	v_mul_f32_e32 v19, 0xbfb8aa3b, v20
	v_mul_f32_e32 v24, 0xbfb8aa3b, v24
	v_mul_f32_e32 v25, 0xbfb8aa3b, v25
	v_exp_f32_e32 v19, v19
	v_mul_f32_e32 v20, 0xbfb8aa3b, v21
	v_exp_f32_e32 v22, v22
	v_exp_f32_e32 v23, v23
	v_exp_f32_e32 v24, v24
	v_exp_f32_e32 v25, v25
	v_exp_f32_e32 v20, v20
	v_rcp_f32_e32 v21, v18
	v_add_f32_e32 v18, 1.0, v19
	v_add_f32_e32 v22, 1.0, v22
	v_add_f32_e32 v23, 1.0, v23
	v_add_f32_e32 v24, 1.0, v24
	v_add_f32_e32 v25, 1.0, v25
	v_rcp_f32_e32 v27, v18
	v_add_f32_e32 v18, 1.0, v20
	v_mul_f32_e32 v14, 0xbfb8aa3b, v14
	v_mul_f32_e32 v10, 0xbfb8aa3b, v10
	v_rcp_f32_e32 v22, v22
	v_rcp_f32_e32 v23, v23
	v_rcp_f32_e32 v24, v24
	v_rcp_f32_e32 v25, v25
	v_rcp_f32_e32 v28, v18
	v_exp_f32_e32 v14, v14
	v_mul_f32_e32 v15, 0xbfb8aa3b, v15
	v_exp_f32_e32 v10, v10
	v_mul_f32_e32 v11, 0xbfb8aa3b, v11
	v_exp_f32_e32 v15, v15
	v_exp_f32_e32 v11, v11
	v_cvt_pk_bf16_f32 v18, v22, v23
	v_cvt_pk_bf16_f32 v19, v24, v25
	v_cvt_pk_bf16_f32 v20, v26, v21
	v_cvt_pk_bf16_f32 v21, v27, v28
	v_add_f32_e32 v14, 1.0, v14
	v_add_f32_e32 v10, 1.0, v10
	flat_store_dwordx4 v[30:31], v[18:21] offset:256
	v_mul_f32_e32 v2, 0xbfb8aa3b, v2
	v_exp_f32_e32 v2, v2
	v_rcp_f32_e32 v19, v14
	v_add_f32_e32 v14, 1.0, v15
	v_mul_f32_e32 v15, 0xbfb8aa3b, v16
	v_rcp_f32_e32 v21, v10
	v_add_f32_e32 v10, 1.0, v11
	v_mul_f32_e32 v11, 0xbfb8aa3b, v12
	v_exp_f32_e32 v15, v15
	v_mul_f32_e32 v16, 0xbfb8aa3b, v17
	v_exp_f32_e32 v11, v11
	v_mul_f32_e32 v12, 0xbfb8aa3b, v13
	v_exp_f32_e32 v16, v16
	v_exp_f32_e32 v12, v12
	v_rcp_f32_e32 v17, v14
	v_add_f32_e32 v14, 1.0, v15
	v_rcp_f32_e32 v13, v10
	v_add_f32_e32 v10, 1.0, v11
	v_rcp_f32_e32 v20, v14
	v_add_f32_e32 v14, 1.0, v16
	v_rcp_f32_e32 v22, v10
	v_add_f32_e32 v10, 1.0, v12
	v_rcp_f32_e32 v16, v14
	v_rcp_f32_e32 v23, v10
	v_mul_f32_e32 v3, 0xbfb8aa3b, v3
	v_exp_f32_e32 v3, v3
	v_add_u32_e32 v18, 0xb0, v162
	v_mad_i64_i32 v[10:11], s[18:19], v18, s20, v[122:123]
	v_lshl_add_u64 v[14:15], v[10:11], 0, v[124:125]
	v_cvt_pk_bf16_f32 v10, v19, v17
	v_cvt_pk_bf16_f32 v11, v20, v16
	v_cvt_pk_bf16_f32 v12, v21, v13
	v_cvt_pk_bf16_f32 v13, v22, v23
	v_add_f32_e32 v2, 1.0, v2
	flat_store_dwordx4 v[14:15], v[10:13]
	v_mul_f32_e32 v6, 0xbfb8aa3b, v6
	v_mul_f32_e32 v7, 0xbfb8aa3b, v7
	v_rcp_f32_e32 v10, v2
	v_add_f32_e32 v2, 1.0, v3
	v_mul_f32_e32 v3, 0xbfb8aa3b, v4
	v_mul_f32_e32 v8, 0xbfb8aa3b, v8
	v_mul_f32_e32 v9, 0xbfb8aa3b, v9
	v_exp_f32_e32 v3, v3
	v_mul_f32_e32 v4, 0xbfb8aa3b, v5
	v_exp_f32_e32 v6, v6
	v_exp_f32_e32 v7, v7
	v_exp_f32_e32 v8, v8
	v_exp_f32_e32 v9, v9
	v_exp_f32_e32 v4, v4
	v_rcp_f32_e32 v5, v2
	v_add_f32_e32 v2, 1.0, v3
	v_add_f32_e32 v6, 1.0, v6
	v_add_f32_e32 v7, 1.0, v7
	v_add_f32_e32 v8, 1.0, v8
	v_add_f32_e32 v9, 1.0, v9
	v_rcp_f32_e32 v11, v2
	v_add_f32_e32 v2, 1.0, v4
	v_rcp_f32_e32 v6, v6
	v_rcp_f32_e32 v7, v7
	v_rcp_f32_e32 v8, v8
	v_rcp_f32_e32 v9, v9
	v_rcp_f32_e32 v12, v2
	v_cvt_pk_bf16_f32 v2, v6, v7
	v_cvt_pk_bf16_f32 v4, v10, v5
	v_cvt_pk_bf16_f32 v3, v8, v9
	v_cvt_pk_bf16_f32 v5, v11, v12
	s_and_b64 vcc, exec, s[2:3]
	s_mov_b64 s[2:3], -1
	flat_store_dwordx4 v[14:15], v[2:5] offset:256
	s_cbranch_vccnz .LBB0_168
	s_andn2_b64 vcc, exec, s[10:11]
	s_cbranch_vccnz .LBB0_167
	s_barrier
	s_branch .LBB0_167

; __device__ __forceinline__ void nt_store16(void* p, const uint4 v) { __builtin_nontemporal_store((u32x4){v.x, v.y, v.z, v.w}, (u32x4*)p); }
; __device__ __forceinline__ uint4 pack_acc8(const f32x4 a, const f32x4 b, float s) { uint4 w; w.x = cvt_pk_bf16(a[0] * s, a[1] * s); w.y = cvt_pk_bf16(a[2] * s, a[3] * s); w.z = cvt_pk_bf16(b[0] * s, b[1] * s); w.w = cvt_pk_bf16(b[2] * s, b[3] * s); return w; }
;     __device__ __forceinline__ void operator()(AccT acc, const Unit& u, int wr, int wc, int fr, int fq) const {
;     ...
;             for (int m = 0; m < 4; ++m) { const size_t row = (size_t)u.z * 1024 + (row0 + ai * HALF + m * 16);
; #pragma unroll
;                 for (int bj = 0; bj < 2; ++bj) nt_store16(PQ + row * 512 + col0 + bj * HALF, pack_acc8(acc[ai][bj][m][0], acc[ai][bj][m][1], 1.0f / 512.0f)); }
.LBB0_386:
	v_lshl_add_u32 v164, s19, 8, v160
	s_ashr_i32 s19, s18, 31
	s_lshl_b64 s[18:19], s[18:19], 20
	v_lshl_or_b32 v138, s66, 8, v162
	v_ashrrev_i32_e32 v165, 31, v164
	s_add_u32 s18, s56, s18
	v_ashrrev_i32_e32 v139, 31, v138
	v_lshlrev_b64 v[158:159], 10, v[164:165]
	s_addc_u32 s19, s57, s19
	v_lshl_add_u64 v[158:159], s[18:19], 0, v[158:159]
	v_lshlrev_b64 v[138:139], 1, v[138:139]
	v_pk_mul_f32 v[62:63], v[62:63], s[38:39] op_sel_hi:[1,0]
	v_pk_mul_f32 v[64:65], v[64:65], s[38:39] op_sel_hi:[1,0]
	v_pk_mul_f32 v[58:59], v[58:59], s[38:39] op_sel_hi:[1,0]
	v_lshl_add_u64 v[158:159], v[158:159], 0, v[138:139]
	v_pk_mul_f32 v[118:119], v[118:119], s[38:39] op_sel_hi:[1,0]
	v_pk_mul_f32 v[120:121], v[120:121], s[38:39] op_sel_hi:[1,0]
	v_pk_mul_f32 v[114:115], v[114:115], s[38:39] op_sel_hi:[1,0]
	v_pk_mul_f32 v[102:103], v[102:103], s[38:39] op_sel_hi:[1,0]
	v_pk_mul_f32 v[104:105], v[104:105], s[38:39] op_sel_hi:[1,0]
	v_pk_mul_f32 v[98:99], v[98:99], s[38:39] op_sel_hi:[1,0]
	v_pk_mul_f32 v[86:87], v[86:87], s[38:39] op_sel_hi:[1,0]
	v_pk_mul_f32 v[88:89], v[88:89], s[38:39] op_sel_hi:[1,0]
	v_pk_mul_f32 v[82:83], v[82:83], s[38:39] op_sel_hi:[1,0]
	v_cvt_pk_bf16_f32 v62, v62, v63
	v_cvt_pk_bf16_f32 v63, v64, v65
	v_cvt_pk_bf16_f32 v64, v58, v59
	v_pk_mul_f32 v[58:59], v[60:61], s[38:39] op_sel_hi:[1,0]
	s_mov_b32 s17, 0x20000
	v_cvt_pk_bf16_f32 v118, v118, v119
	v_cvt_pk_bf16_f32 v119, v120, v121
	v_cvt_pk_bf16_f32 v120, v114, v115
	v_pk_mul_f32 v[114:115], v[116:117], s[38:39] op_sel_hi:[1,0]
	v_cvt_pk_bf16_f32 v102, v102, v103
	v_cvt_pk_bf16_f32 v103, v104, v105
	v_cvt_pk_bf16_f32 v104, v98, v99
	v_pk_mul_f32 v[98:99], v[100:101], s[38:39] op_sel_hi:[1,0]
	v_cvt_pk_bf16_f32 v86, v86, v87
	v_cvt_pk_bf16_f32 v87, v88, v89
	v_cvt_pk_bf16_f32 v88, v82, v83
	v_pk_mul_f32 v[82:83], v[84:85], s[38:39] op_sel_hi:[1,0]
	v_cvt_pk_bf16_f32 v65, v58, v59
	v_add_co_u32_e32 v58, vcc, s17, v158
	v_pk_mul_f32 v[46:47], v[46:47], s[38:39] op_sel_hi:[1,0]
	v_pk_mul_f32 v[48:49], v[48:49], s[38:39] op_sel_hi:[1,0]
	v_pk_mul_f32 v[42:43], v[42:43], s[38:39] op_sel_hi:[1,0]
	v_cvt_pk_bf16_f32 v121, v114, v115
	v_or_b32_e32 v114, 16, v164
	v_cvt_pk_bf16_f32 v105, v98, v99
	v_or_b32_e32 v98, 32, v164
	v_cvt_pk_bf16_f32 v89, v82, v83
	v_or_b32_e32 v82, 48, v164
	v_addc_co_u32_e32 v59, vcc, 0, v159, vcc
	v_cvt_pk_bf16_f32 v46, v46, v47
	v_cvt_pk_bf16_f32 v47, v48, v49
	v_cvt_pk_bf16_f32 v48, v42, v43
	v_pk_mul_f32 v[42:43], v[44:45], s[38:39] op_sel_hi:[1,0]
	s_mov_b32 s17, 0x24000
	v_ashrrev_i32_e32 v115, 31, v114
	v_ashrrev_i32_e32 v99, 31, v98
	v_ashrrev_i32_e32 v83, 31, v82
	v_cvt_pk_bf16_f32 v49, v42, v43
	v_add_co_u32_e32 v42, vcc, s17, v158
	v_pk_mul_f32 v[30:31], v[30:31], s[38:39] op_sel_hi:[1,0]
	v_pk_mul_f32 v[32:33], v[32:33], s[38:39] op_sel_hi:[1,0]
	v_pk_mul_f32 v[26:27], v[26:27], s[38:39] op_sel_hi:[1,0]
	v_lshlrev_b64 v[114:115], 10, v[114:115]
	v_lshlrev_b64 v[98:99], 10, v[98:99]
	v_lshlrev_b64 v[82:83], 10, v[82:83]
	v_pk_mul_f32 v[70:71], v[70:71], s[38:39] op_sel_hi:[1,0]
	v_pk_mul_f32 v[72:73], v[72:73], s[38:39] op_sel_hi:[1,0]
	v_pk_mul_f32 v[66:67], v[66:67], s[38:39] op_sel_hi:[1,0]
	v_addc_co_u32_e32 v43, vcc, 0, v159, vcc
	v_cvt_pk_bf16_f32 v30, v30, v31
	v_cvt_pk_bf16_f32 v31, v32, v33
	v_cvt_pk_bf16_f32 v32, v26, v27
	v_pk_mul_f32 v[26:27], v[28:29], s[38:39] op_sel_hi:[1,0]
	s_mov_b32 s17, 0x28000
	v_lshl_add_u64 v[114:115], s[18:19], 0, v[114:115]
	v_lshl_add_u64 v[98:99], s[18:19], 0, v[98:99]
	v_lshl_add_u64 v[82:83], s[18:19], 0, v[82:83]
	v_cvt_pk_bf16_f32 v70, v70, v71
	v_cvt_pk_bf16_f32 v71, v72, v73
	v_cvt_pk_bf16_f32 v72, v66, v67
	v_pk_mul_f32 v[66:67], v[68:69], s[38:39] op_sel_hi:[1,0]
	s_mov_b64 s[18:19], 0x20000
	v_pk_mul_f32 v[54:55], v[54:55], s[38:39] op_sel_hi:[1,0]
	v_pk_mul_f32 v[56:57], v[56:57], s[38:39] op_sel_hi:[1,0]
	v_pk_mul_f32 v[50:51], v[50:51], s[38:39] op_sel_hi:[1,0]
	v_cvt_pk_bf16_f32 v33, v26, v27
	v_add_co_u32_e32 v26, vcc, s17, v158
	v_pk_mul_f32 v[14:15], v[14:15], s[38:39] op_sel_hi:[1,0]
	v_pk_mul_f32 v[16:17], v[16:17], s[38:39] op_sel_hi:[1,0]
	v_pk_mul_f32 v[10:11], v[10:11], s[38:39] op_sel_hi:[1,0]
	v_cvt_pk_bf16_f32 v73, v66, v67
	v_lshl_add_u64 v[66:67], v[158:159], 0, s[18:19]
	v_cvt_pk_bf16_f32 v54, v54, v55
	v_cvt_pk_bf16_f32 v55, v56, v57
	v_cvt_pk_bf16_f32 v56, v50, v51
; __device__ __forceinline__ void nt_store16(void* p, const uint4 v) { __builtin_nontemporal_store((u32x4){v.x, v.y, v.z, v.w}, (u32x4*)p); }
; __device__ __forceinline__ uint4 pack_acc8(const f32x4 a, const f32x4 b, float s) { uint4 w; w.x = cvt_pk_bf16(a[0] * s, a[1] * s); w.y = cvt_pk_bf16(a[2] * s, a[3] * s); w.z = cvt_pk_bf16(b[0] * s, b[1] * s); w.w = cvt_pk_bf16(b[2] * s, b[3] * s); return w; }
;     __device__ __forceinline__ void operator()(AccT acc, const Unit& u, int wr, int wc, int fr, int fq) const {
;     ...
;             for (int m = 0; m < 4; ++m) { const size_t row = (size_t)u.z * 1024 + (row0 + ai * HALF + m * 16);
; #pragma unroll
;                 for (int bj = 0; bj < 2; ++bj) nt_store16(PQ + row * 512 + col0 + bj * HALF, pack_acc8(acc[ai][bj][m][0], acc[ai][bj][m][1], 1.0f / 512.0f)); }
	v_pk_mul_f32 v[50:51], v[52:53], s[38:39] op_sel_hi:[1,0]
	s_mov_b64 s[18:19], 0x24000
	v_pk_mul_f32 v[38:39], v[38:39], s[38:39] op_sel_hi:[1,0]
	v_pk_mul_f32 v[40:41], v[40:41], s[38:39] op_sel_hi:[1,0]
	v_pk_mul_f32 v[34:35], v[34:35], s[38:39] op_sel_hi:[1,0]
	v_addc_co_u32_e32 v27, vcc, 0, v159, vcc
	v_cvt_pk_bf16_f32 v14, v14, v15
	v_cvt_pk_bf16_f32 v15, v16, v17
	v_cvt_pk_bf16_f32 v16, v10, v11
	v_pk_mul_f32 v[10:11], v[12:13], s[38:39] op_sel_hi:[1,0]
	s_mov_b32 s17, 0x2c000
	v_pk_mul_f32 v[126:127], v[126:127], s[38:39] op_sel_hi:[1,0]
	v_pk_mul_f32 v[128:129], v[128:129], s[38:39] op_sel_hi:[1,0]
	v_pk_mul_f32 v[122:123], v[122:123], s[38:39] op_sel_hi:[1,0]
	v_pk_mul_f32 v[110:111], v[110:111], s[38:39] op_sel_hi:[1,0]
	v_pk_mul_f32 v[112:113], v[112:113], s[38:39] op_sel_hi:[1,0]
	v_pk_mul_f32 v[106:107], v[106:107], s[38:39] op_sel_hi:[1,0]
	v_pk_mul_f32 v[94:95], v[94:95], s[38:39] op_sel_hi:[1,0]
	v_pk_mul_f32 v[96:97], v[96:97], s[38:39] op_sel_hi:[1,0]
	v_pk_mul_f32 v[90:91], v[90:91], s[38:39] op_sel_hi:[1,0]
	v_pk_mul_f32 v[78:79], v[78:79], s[38:39] op_sel_hi:[1,0]
	v_pk_mul_f32 v[80:81], v[80:81], s[38:39] op_sel_hi:[1,0]
	v_pk_mul_f32 v[74:75], v[74:75], s[38:39] op_sel_hi:[1,0]
	v_cvt_pk_bf16_f32 v57, v50, v51
	v_lshl_add_u64 v[50:51], v[158:159], 0, s[18:19]
	v_cvt_pk_bf16_f32 v38, v38, v39
	v_cvt_pk_bf16_f32 v39, v40, v41
	v_cvt_pk_bf16_f32 v40, v34, v35
	v_pk_mul_f32 v[34:35], v[36:37], s[38:39] op_sel_hi:[1,0]
	s_mov_b64 s[18:19], 0x28000
	v_pk_mul_f32 v[22:23], v[22:23], s[38:39] op_sel_hi:[1,0]
	v_pk_mul_f32 v[24:25], v[24:25], s[38:39] op_sel_hi:[1,0]
	v_pk_mul_f32 v[18:19], v[18:19], s[38:39] op_sel_hi:[1,0]
	v_cvt_pk_bf16_f32 v17, v10, v11
	v_add_co_u32_e32 v10, vcc, s17, v158
	v_pk_mul_f32 v[6:7], v[6:7], s[38:39] op_sel_hi:[1,0]
	v_pk_mul_f32 v[8:9], v[8:9], s[38:39] op_sel_hi:[1,0]
	v_pk_mul_f32 v[2:3], v[2:3], s[38:39] op_sel_hi:[1,0]
	v_cvt_pk_bf16_f32 v126, v126, v127
	v_cvt_pk_bf16_f32 v127, v128, v129
	v_cvt_pk_bf16_f32 v128, v122, v123
	v_pk_mul_f32 v[122:123], v[124:125], s[38:39] op_sel_hi:[1,0]
	v_cvt_pk_bf16_f32 v110, v110, v111
	v_cvt_pk_bf16_f32 v111, v112, v113
	v_cvt_pk_bf16_f32 v112, v106, v107
	v_pk_mul_f32 v[106:107], v[108:109], s[38:39] op_sel_hi:[1,0]
	v_cvt_pk_bf16_f32 v94, v94, v95
	v_cvt_pk_bf16_f32 v95, v96, v97
	v_cvt_pk_bf16_f32 v96, v90, v91
	v_pk_mul_f32 v[90:91], v[92:93], s[38:39] op_sel_hi:[1,0]
	v_cvt_pk_bf16_f32 v78, v78, v79
	v_cvt_pk_bf16_f32 v79, v80, v81
	v_cvt_pk_bf16_f32 v80, v74, v75
	v_pk_mul_f32 v[74:75], v[76:77], s[38:39] op_sel_hi:[1,0]
	v_cvt_pk_bf16_f32 v41, v34, v35
	v_lshl_add_u64 v[34:35], v[158:159], 0, s[18:19]
	v_cvt_pk_bf16_f32 v22, v22, v23
	v_cvt_pk_bf16_f32 v23, v24, v25
	v_cvt_pk_bf16_f32 v24, v18, v19
	v_pk_mul_f32 v[18:19], v[20:21], s[38:39] op_sel_hi:[1,0]
	s_mov_b64 s[18:19], 0x2c000
	v_addc_co_u32_e32 v11, vcc, 0, v159, vcc
	v_cvt_pk_bf16_f32 v6, v6, v7
	v_cvt_pk_bf16_f32 v7, v8, v9
	v_cvt_pk_bf16_f32 v8, v2, v3
	v_pk_mul_f32 v[2:3], v[4:5], s[38:39] op_sel_hi:[1,0]
	v_cvt_pk_bf16_f32 v129, v122, v123
	v_lshl_add_u64 v[114:115], v[114:115], 0, v[138:139]
	v_cvt_pk_bf16_f32 v113, v106, v107
	v_lshl_add_u64 v[98:99], v[98:99], 0, v[138:139]
	v_cvt_pk_bf16_f32 v97, v90, v91
	v_lshl_add_u64 v[82:83], v[82:83], 0, v[138:139]
	v_cvt_pk_bf16_f32 v81, v74, v75
	v_cvt_pk_bf16_f32 v25, v18, v19
	v_lshl_add_u64 v[18:19], v[158:159], 0, s[18:19]
	v_cvt_pk_bf16_f32 v9, v2, v3
	s_and_b64 vcc, exec, s[2:3]
	s_mov_b64 s[2:3], -1
	flat_store_dwordx4 v[158:159], v[126:129]
	flat_store_dwordx4 v[158:159], v[118:121] offset:256
	flat_store_dwordx4 v[114:115], v[110:113]
	flat_store_dwordx4 v[114:115], v[102:105] offset:256
	flat_store_dwordx4 v[98:99], v[94:97]
	flat_store_dwordx4 v[98:99], v[86:89] offset:256
	flat_store_dwordx4 v[82:83], v[78:81]
	flat_store_dwordx4 v[82:83], v[70:73] offset:256
	flat_store_dwordx4 v[58:59], v[62:65]
	flat_store_dwordx4 v[66:67], v[54:57] offset:256
	flat_store_dwordx4 v[42:43], v[46:49]
	flat_store_dwordx4 v[50:51], v[38:41] offset:256
	flat_store_dwordx4 v[26:27], v[30:33]
	flat_store_dwordx4 v[34:35], v[22:25] offset:256
	flat_store_dwordx4 v[10:11], v[14:17]
	flat_store_dwordx4 v[18:19], v[6:9] offset:256
	s_cbranch_vccnz .LBB0_374
	s_andn2_b64 vcc, exec, s[10:11]
	s_cbranch_vccnz .LBB0_373
	s_barrier
	s_branch .LBB0_373

; __device__ __forceinline__ void nt_store16(void* p, const uint4 v) { __builtin_nontemporal_store((u32x4){v.x, v.y, v.z, v.w}, (u32x4*)p); }
; __device__ __forceinline__ uint4 pack_acc8(const f32x4 a, const f32x4 b, float s) { uint4 w; w.x = cvt_pk_bf16(a[0] * s, a[1] * s); w.y = cvt_pk_bf16(a[2] * s, a[3] * s); w.z = cvt_pk_bf16(b[0] * s, b[1] * s); w.w = cvt_pk_bf16(b[2] * s, b[3] * s); return w; }
;     __device__ __forceinline__ void operator()(AccT acc, const Unit& u, int wr, int wc, int fr, int fq) const {
;     ...
;             for (int m = 0; m < 4; ++m) { const size_t row = (size_t)(row0 + ai * HALF + m * 16);
; #pragma unroll
;                 for (int bj = 0; bj < 2; ++bj) { const int c = col0 + bj * HALF;
;                     bf16_t* dst = (c < ZGC) ? (ZG + row * ZGC + c) : (ZR + row * ZRC + (c - ZGC));
;                     nt_store16(dst, pack_acc8(acc[ai][bj][m][0], acc[ai][bj][m][1], 1.0f)); } }
.LBB0_470:
	v_lshl_add_u32 v183, s67, 8, v179
	v_mad_i64_i32 v[138:139], s[4:5], v183, s46, 0
	v_lshl_or_b32 v160, s66, 8, v181
	s_movk_i32 s4, 0x61f
	v_cmp_lt_i32_e32 vcc, s4, v160
	v_lshl_add_u64 v[162:163], s[14:15], 0, v[138:139]
	s_and_saveexec_b64 s[4:5], vcc
	s_xor_b64 s[4:5], exec, s[4:5]
	v_mov_b32_e32 v161, v1
	s_movk_i32 s24, 0xf3c0
	v_lshl_add_u64 v[138:139], v[160:161], 1, v[162:163]
	s_mov_b32 s25, -1
	v_lshl_add_u64 v[166:167], v[138:139], 0, s[24:25]
	s_or_saveexec_b64 s[4:5], s[4:5]
	v_mad_i64_i32 v[138:139], s[24:25], v183, s47, 0
	v_readlane_b32 s24, v254, 35
	v_readlane_b32 s25, v254, 36
	v_ashrrev_i32_e32 v161, 31, v160
	s_mov_b64 s[66:67], 0x100
	v_lshl_add_u64 v[164:165], s[24:25], 0, v[138:139]
	s_xor_b64 exec, exec, s[4:5]
	v_lshl_add_u64 v[166:167], v[160:161], 1, v[164:165]
	s_or_b64 exec, exec, s[4:5]
	v_or_b32_e32 v0, 0x80, v160
	s_movk_i32 s4, 0x61f
	v_cvt_pk_bf16_f32 v122, v122, v123
	v_cvt_pk_bf16_f32 v123, v124, v125
	v_cvt_pk_bf16_f32 v124, v126, v127
	v_cvt_pk_bf16_f32 v125, v128, v129
	v_cmp_lt_i32_e64 s[4:5], s4, v0
	flat_store_dwordx4 v[166:167], v[122:125]
	s_and_saveexec_b64 s[24:25], s[4:5]
	s_xor_b64 s[24:25], exec, s[24:25]
	v_mov_b32_e32 v0, v160
	s_movk_i32 s34, 0xf4c0
	v_lshl_add_u64 v[122:123], v[0:1], 1, v[162:163]
	s_mov_b32 s35, -1
	v_lshl_add_u64 v[122:123], v[122:123], 0, s[34:35]
	s_andn2_saveexec_b64 s[24:25], s[24:25]
	v_lshl_add_u64 v[122:123], v[160:161], 1, v[164:165]
	v_lshl_add_u64 v[122:123], v[122:123], 0, s[66:67]
	s_or_b64 exec, exec, s[24:25]
	v_cvt_pk_bf16_f32 v118, v118, v119
	v_cvt_pk_bf16_f32 v119, v120, v121
	v_cvt_pk_bf16_f32 v121, v116, v117
	v_or_b32_e32 v116, 16, v183
	v_cvt_pk_bf16_f32 v120, v114, v115
	v_mad_i64_i32 v[114:115], s[24:25], v116, s46, 0
	v_lshl_add_u64 v[114:115], s[14:15], 0, v[114:115]
	flat_store_dwordx4 v[122:123], v[118:121]
	s_and_saveexec_b64 s[24:25], vcc
	s_xor_b64 s[24:25], exec, s[24:25]
	v_mov_b32_e32 v0, v160
	s_movk_i32 s34, 0xf3c0
	v_lshl_add_u64 v[118:119], v[0:1], 1, v[114:115]
	s_mov_b32 s35, -1
	v_lshl_add_u64 v[118:119], v[118:119], 0, s[34:35]
	s_or_saveexec_b64 s[24:25], s[24:25]
	v_mad_i64_i32 v[116:117], s[34:35], v116, s47, 0
	v_readlane_b32 s34, v254, 35
	v_readlane_b32 s35, v254, 36
	s_nop 1
	v_lshl_add_u64 v[116:117], s[34:35], 0, v[116:117]
	s_xor_b64 exec, exec, s[24:25]
	v_lshl_add_u64 v[118:119], v[160:161], 1, v[116:117]
	s_or_b64 exec, exec, s[24:25]
	v_cvt_pk_bf16_f32 v110, v110, v111
	v_cvt_pk_bf16_f32 v111, v112, v113
	v_cvt_pk_bf16_f32 v112, v106, v107
	v_cvt_pk_bf16_f32 v113, v108, v109
	flat_store_dwordx4 v[118:119], v[110:113]
	s_and_saveexec_b64 s[24:25], s[4:5]
	s_xor_b64 s[24:25], exec, s[24:25]
	v_mov_b32_e32 v0, v160
	s_movk_i32 s34, 0xf4c0
	v_lshl_add_u64 v[106:107], v[0:1], 1, v[114:115]
	s_mov_b32 s35, -1
	v_lshl_add_u64 v[106:107], v[106:107], 0, s[34:35]
	s_andn2_saveexec_b64 s[24:25], s[24:25]
	v_lshl_add_u64 v[106:107], v[160:161], 1, v[116:117]
	v_lshl_add_u64 v[106:107], v[106:107], 0, s[66:67]
	s_or_b64 exec, exec, s[24:25]
	v_cvt_pk_bf16_f32 v102, v102, v103
	v_cvt_pk_bf16_f32 v103, v104, v105
	v_cvt_pk_bf16_f32 v105, v100, v101
	v_or_b32_e32 v100, 32, v183
	v_cvt_pk_bf16_f32 v104, v98, v99
	v_mad_i64_i32 v[98:99], s[24:25], v100, s46, 0
	v_lshl_add_u64 v[98:99], s[14:15], 0, v[98:99]
	flat_store_dwordx4 v[106:107], v[102:105]
	s_and_saveexec_b64 s[24:25], vcc
	s_xor_b64 s[24:25], exec, s[24:25]
	v_mov_b32_e32 v0, v160
	s_movk_i32 s34, 0xf3c0
	v_lshl_add_u64 v[102:103], v[0:1], 1, v[98:99]
	s_mov_b32 s35, -1
	v_lshl_add_u64 v[102:103], v[102:103], 0, s[34:35]
	s_or_saveexec_b64 s[24:25], s[24:25]
	v_mad_i64_i32 v[100:101], s[34:35], v100, s47, 0
	v_readlane_b32 s34, v254, 35
	v_readlane_b32 s35, v254, 36
	s_nop 1
	v_lshl_add_u64 v[100:101], s[34:35], 0, v[100:101]
	s_xor_b64 exec, exec, s[24:25]
	v_lshl_add_u64 v[102:103], v[160:161], 1, v[100:101]
	s_or_b64 exec, exec, s[24:25]
	v_cvt_pk_bf16_f32 v94, v94, v95
	v_cvt_pk_bf16_f32 v95, v96, v97
	v_cvt_pk_bf16_f32 v96, v90, v91
	v_cvt_pk_bf16_f32 v97, v92, v93
	flat_store_dwordx4 v[102:103], v[94:97]
	s_and_saveexec_b64 s[24:25], s[4:5]
	s_xor_b64 s[24:25], exec, s[24:25]
	v_mov_b32_e32 v0, v160
	s_movk_i32 s34, 0xf4c0
	v_lshl_add_u64 v[90:91], v[0:1], 1, v[98:99]
	s_mov_b32 s35, -1
	v_lshl_add_u64 v[90:91], v[90:91], 0, s[34:35]
	s_andn2_saveexec_b64 s[24:25], s[24:25]
	v_lshl_add_u64 v[90:91], v[160:161], 1, v[100:101]
	v_lshl_add_u64 v[90:91], v[90:91], 0, s[66:67]
	s_or_b64 exec, exec, s[24:25]
	v_cvt_pk_bf16_f32 v86, v86, v87
	v_cvt_pk_bf16_f32 v87, v88, v89
	v_cvt_pk_bf16_f32 v89, v84, v85
	v_or_b32_e32 v84, 48, v183
	v_cvt_pk_bf16_f32 v88, v82, v83
	v_mad_i64_i32 v[82:83], s[24:25], v84, s46, 0
	v_lshl_add_u64 v[82:83], s[14:15], 0, v[82:83]
	flat_store_dwordx4 v[90:91], v[86:89]
	s_and_saveexec_b64 s[24:25], vcc
	s_xor_b64 s[24:25], exec, s[24:25]
	v_mov_b32_e32 v0, v160
	s_movk_i32 s34, 0xf3c0
	v_lshl_add_u64 v[86:87], v[0:1], 1, v[82:83]
	s_mov_b32 s35, -1
	v_lshl_add_u64 v[86:87], v[86:87], 0, s[34:35]
	s_or_saveexec_b64 s[24:25], s[24:25]
	v_mad_i64_i32 v[84:85], s[34:35], v84, s47, 0
	v_readlane_b32 s34, v254, 35
	v_readlane_b32 s35, v254, 36
	s_nop 1
	v_lshl_add_u64 v[84:85], s[34:35], 0, v[84:85]
	s_xor_b64 exec, exec, s[24:25]
	v_lshl_add_u64 v[86:87], v[160:161], 1, v[84:85]
	s_or_b64 exec, exec, s[24:25]
	v_cvt_pk_bf16_f32 v78, v78, v79
	v_cvt_pk_bf16_f32 v79, v80, v81
	v_cvt_pk_bf16_f32 v80, v74, v75
	v_cvt_pk_bf16_f32 v81, v76, v77
	flat_store_dwordx4 v[86:87], v[78:81]
	s_and_saveexec_b64 s[24:25], s[4:5]
	s_xor_b64 s[24:25], exec, s[24:25]
	v_mov_b32_e32 v0, v160
	s_movk_i32 s34, 0xf4c0
	v_lshl_add_u64 v[74:75], v[0:1], 1, v[82:83]
; __device__ __forceinline__ void nt_store16(void* p, const uint4 v) { __builtin_nontemporal_store((u32x4){v.x, v.y, v.z, v.w}, (u32x4*)p); }
; __device__ __forceinline__ uint4 pack_acc8(const f32x4 a, const f32x4 b, float s) { uint4 w; w.x = cvt_pk_bf16(a[0] * s, a[1] * s); w.y = cvt_pk_bf16(a[2] * s, a[3] * s); w.z = cvt_pk_bf16(b[0] * s, b[1] * s); w.w = cvt_pk_bf16(b[2] * s, b[3] * s); return w; }
;     __device__ __forceinline__ void operator()(AccT acc, const Unit& u, int wr, int wc, int fr, int fq) const {
;     ...
;             for (int m = 0; m < 4; ++m) { const size_t row = (size_t)(row0 + ai * HALF + m * 16);
; #pragma unroll
;                 for (int bj = 0; bj < 2; ++bj) { const int c = col0 + bj * HALF;
;                     bf16_t* dst = (c < ZGC) ? (ZG + row * ZGC + c) : (ZR + row * ZRC + (c - ZGC));
;                     nt_store16(dst, pack_acc8(acc[ai][bj][m][0], acc[ai][bj][m][1], 1.0f)); } }
	s_mov_b32 s35, -1
	v_lshl_add_u64 v[74:75], v[74:75], 0, s[34:35]
	s_andn2_saveexec_b64 s[24:25], s[24:25]
	v_lshl_add_u64 v[74:75], v[160:161], 1, v[84:85]
	v_lshl_add_u64 v[74:75], v[74:75], 0, s[66:67]
	s_or_b64 exec, exec, s[24:25]
	v_cvt_pk_bf16_f32 v70, v70, v71
	v_cvt_pk_bf16_f32 v71, v72, v73
	v_cvt_pk_bf16_f32 v73, v68, v69
	v_add_u32_e32 v68, 0x80, v183
	v_cvt_pk_bf16_f32 v72, v66, v67
	v_mad_i64_i32 v[66:67], s[24:25], v68, s46, 0
	v_lshl_add_u64 v[66:67], s[14:15], 0, v[66:67]
	flat_store_dwordx4 v[74:75], v[70:73]
	s_and_saveexec_b64 s[24:25], vcc
	s_xor_b64 s[24:25], exec, s[24:25]
	v_mov_b32_e32 v0, v160
	s_movk_i32 s34, 0xf3c0
	v_lshl_add_u64 v[70:71], v[0:1], 1, v[66:67]
	s_mov_b32 s35, -1
	v_lshl_add_u64 v[70:71], v[70:71], 0, s[34:35]
	s_or_saveexec_b64 s[24:25], s[24:25]
	v_mad_i64_i32 v[68:69], s[34:35], v68, s47, 0
	v_readlane_b32 s34, v254, 35
	v_readlane_b32 s35, v254, 36
	s_nop 1
	v_lshl_add_u64 v[68:69], s[34:35], 0, v[68:69]
	s_xor_b64 exec, exec, s[24:25]
	v_lshl_add_u64 v[70:71], v[160:161], 1, v[68:69]
	s_or_b64 exec, exec, s[24:25]
	v_cvt_pk_bf16_f32 v62, v62, v63
	v_cvt_pk_bf16_f32 v63, v64, v65
	v_cvt_pk_bf16_f32 v64, v58, v59
	v_cvt_pk_bf16_f32 v65, v60, v61
	flat_store_dwordx4 v[70:71], v[62:65]
	s_and_saveexec_b64 s[24:25], s[4:5]
	s_xor_b64 s[24:25], exec, s[24:25]
	v_mov_b32_e32 v0, v160
	s_movk_i32 s34, 0xf4c0
	v_lshl_add_u64 v[58:59], v[0:1], 1, v[66:67]
	s_mov_b32 s35, -1
	v_lshl_add_u64 v[58:59], v[58:59], 0, s[34:35]
	s_andn2_saveexec_b64 s[24:25], s[24:25]
	v_lshl_add_u64 v[58:59], v[160:161], 1, v[68:69]
	v_lshl_add_u64 v[58:59], v[58:59], 0, s[66:67]
	s_or_b64 exec, exec, s[24:25]
	v_cvt_pk_bf16_f32 v54, v54, v55
	v_cvt_pk_bf16_f32 v55, v56, v57
	v_cvt_pk_bf16_f32 v57, v52, v53
	v_add_u32_e32 v52, 0x90, v183
	v_cvt_pk_bf16_f32 v56, v50, v51
	v_mad_i64_i32 v[50:51], s[24:25], v52, s46, 0
	v_lshl_add_u64 v[50:51], s[14:15], 0, v[50:51]
	flat_store_dwordx4 v[58:59], v[54:57]
	s_and_saveexec_b64 s[24:25], vcc
	s_xor_b64 s[24:25], exec, s[24:25]
	v_mov_b32_e32 v0, v160
	s_movk_i32 s34, 0xf3c0
	v_lshl_add_u64 v[54:55], v[0:1], 1, v[50:51]
	s_mov_b32 s35, -1
	v_lshl_add_u64 v[54:55], v[54:55], 0, s[34:35]
	s_or_saveexec_b64 s[24:25], s[24:25]
	v_mad_i64_i32 v[52:53], s[34:35], v52, s47, 0
	v_readlane_b32 s34, v254, 35
	v_readlane_b32 s35, v254, 36
	s_nop 1
	v_lshl_add_u64 v[52:53], s[34:35], 0, v[52:53]
	s_xor_b64 exec, exec, s[24:25]
	v_lshl_add_u64 v[54:55], v[160:161], 1, v[52:53]
	s_or_b64 exec, exec, s[24:25]
	v_cvt_pk_bf16_f32 v46, v46, v47
	v_cvt_pk_bf16_f32 v47, v48, v49
	v_cvt_pk_bf16_f32 v48, v42, v43
	v_cvt_pk_bf16_f32 v49, v44, v45
	flat_store_dwordx4 v[54:55], v[46:49]
	s_and_saveexec_b64 s[24:25], s[4:5]
	s_xor_b64 s[24:25], exec, s[24:25]
	v_mov_b32_e32 v0, v160
	s_movk_i32 s34, 0xf4c0
	v_lshl_add_u64 v[42:43], v[0:1], 1, v[50:51]
	s_mov_b32 s35, -1
	v_lshl_add_u64 v[42:43], v[42:43], 0, s[34:35]
	s_andn2_saveexec_b64 s[24:25], s[24:25]
	v_lshl_add_u64 v[42:43], v[160:161], 1, v[52:53]
	v_lshl_add_u64 v[42:43], v[42:43], 0, s[66:67]
	s_or_b64 exec, exec, s[24:25]
	v_cvt_pk_bf16_f32 v38, v38, v39
	v_cvt_pk_bf16_f32 v39, v40, v41
	v_cvt_pk_bf16_f32 v41, v36, v37
	v_add_u32_e32 v36, 0xa0, v183
	v_cvt_pk_bf16_f32 v40, v34, v35
	v_mad_i64_i32 v[34:35], s[24:25], v36, s46, 0
	v_lshl_add_u64 v[34:35], s[14:15], 0, v[34:35]
	flat_store_dwordx4 v[42:43], v[38:41]
	s_and_saveexec_b64 s[24:25], vcc
	s_xor_b64 s[24:25], exec, s[24:25]
	v_mov_b32_e32 v0, v160
	s_movk_i32 s34, 0xf3c0
	v_lshl_add_u64 v[38:39], v[0:1], 1, v[34:35]
	s_mov_b32 s35, -1
	v_lshl_add_u64 v[38:39], v[38:39], 0, s[34:35]
	s_or_saveexec_b64 s[24:25], s[24:25]
	v_mad_i64_i32 v[36:37], s[34:35], v36, s47, 0
	v_readlane_b32 s34, v254, 35
	v_readlane_b32 s35, v254, 36
	s_nop 1
	v_lshl_add_u64 v[36:37], s[34:35], 0, v[36:37]
	s_xor_b64 exec, exec, s[24:25]
	v_lshl_add_u64 v[38:39], v[160:161], 1, v[36:37]
	s_or_b64 exec, exec, s[24:25]
	v_cvt_pk_bf16_f32 v30, v30, v31
	v_cvt_pk_bf16_f32 v31, v32, v33
	v_cvt_pk_bf16_f32 v32, v26, v27
	v_cvt_pk_bf16_f32 v33, v28, v29
	flat_store_dwordx4 v[38:39], v[30:33]
	s_and_saveexec_b64 s[24:25], s[4:5]
	s_xor_b64 s[24:25], exec, s[24:25]
	v_mov_b32_e32 v0, v160
	s_movk_i32 s34, 0xf4c0
	v_lshl_add_u64 v[26:27], v[0:1], 1, v[34:35]
	s_mov_b32 s35, -1
	v_lshl_add_u64 v[26:27], v[26:27], 0, s[34:35]
	s_andn2_saveexec_b64 s[24:25], s[24:25]
	v_lshl_add_u64 v[26:27], v[160:161], 1, v[36:37]
	v_lshl_add_u64 v[26:27], v[26:27], 0, s[66:67]
	s_or_b64 exec, exec, s[24:25]
	v_cvt_pk_bf16_f32 v22, v22, v23
	v_cvt_pk_bf16_f32 v23, v24, v25
	v_cvt_pk_bf16_f32 v25, v20, v21
	v_add_u32_e32 v20, 0xb0, v183
	v_cvt_pk_bf16_f32 v24, v18, v19
	v_mad_i64_i32 v[18:19], s[24:25], v20, s46, 0
	v_lshl_add_u64 v[18:19], s[14:15], 0, v[18:19]
	flat_store_dwordx4 v[26:27], v[22:25]
	s_and_saveexec_b64 s[24:25], vcc
	s_xor_b64 s[24:25], exec, s[24:25]
	v_mov_b32_e32 v0, v160
	s_movk_i32 s34, 0xf3c0
	v_lshl_add_u64 v[22:23], v[0:1], 1, v[18:19]
	s_mov_b32 s35, -1
	v_lshl_add_u64 v[22:23], v[22:23], 0, s[34:35]
	s_or_saveexec_b64 s[24:25], s[24:25]
	v_mad_i64_i32 v[20:21], s[34:35], v20, s47, 0
	v_readlane_b32 s34, v254, 35
	v_readlane_b32 s35, v254, 36
	s_nop 1
	v_lshl_add_u64 v[20:21], s[34:35], 0, v[20:21]
	s_xor_b64 exec, exec, s[24:25]
	v_lshl_add_u64 v[22:23], v[160:161], 1, v[20:21]
	s_or_b64 exec, exec, s[24:25]
	v_cvt_pk_bf16_f32 v14, v14, v15
	v_cvt_pk_bf16_f32 v15, v16, v17
	v_cvt_pk_bf16_f32 v16, v10, v11
	v_cvt_pk_bf16_f32 v17, v12, v13
	flat_store_dwordx4 v[22:23], v[14:17]
	s_and_saveexec_b64 s[24:25], s[4:5]
	s_xor_b64 s[4:5], exec, s[24:25]
	v_mov_b32_e32 v161, v1
	s_movk_i32 s24, 0xf4c0
	v_lshl_add_u64 v[10:11], v[160:161], 1, v[18:19]
	s_mov_b32 s25, -1
	v_lshl_add_u64 v[10:11], v[10:11], 0, s[24:25]
	s_andn2_saveexec_b64 s[4:5], s[4:5]
	v_lshl_add_u64 v[10:11], v[160:161], 1, v[20:21]
	v_lshl_add_u64 v[10:11], v[10:11], 0, s[66:67]
	s_or_b64 exec, exec, s[4:5]
	v_cvt_pk_bf16_f32 v6, v6, v7
	v_cvt_pk_bf16_f32 v7, v8, v9
	v_cvt_pk_bf16_f32 v8, v2, v3
	v_cvt_pk_bf16_f32 v9, v4, v5
	s_and_b64 vcc, exec, s[2:3]
	s_mov_b64 s[2:3], -1
	flat_store_dwordx4 v[10:11], v[6:9]
	s_cbranch_vccnz .LBB0_457
	s_andn2_b64 vcc, exec, s[12:13]
	s_cbranch_vccnz .LBB0_456
	s_barrier
	s_branch .LBB0_456

; __device__ __forceinline__ void nt_store16(void* p, const uint4 v) { __builtin_nontemporal_store((u32x4){v.x, v.y, v.z, v.w}, (u32x4*)p); }
; __device__ __forceinline__ uint4 pack_acc8(const f32x4 a, const f32x4 b, float s) { uint4 w; w.x = cvt_pk_bf16(a[0] * s, a[1] * s); w.y = cvt_pk_bf16(a[2] * s, a[3] * s); w.z = cvt_pk_bf16(b[0] * s, b[1] * s); w.w = cvt_pk_bf16(b[2] * s, b[3] * s); return w; }
;     __device__ __forceinline__ void operator()(AccT acc, const Unit& u, int wr, int wc, int fr, int fq) const {
;     ...
;             for (int m = 0; m < 4; ++m) { const int row = row0 + ai * HALF + m * 16;
; #pragma unroll
;                 for (int bj = 0; bj < 2; ++bj) { const int c = col0 + bj * HALF; const int b = c >> 11, s = c & 2047;
;                     nt_store16(FT + ((size_t)((b * 2 + (row & 1)) * 512 + (row >> 1)) * SEQ_ + s), pack_acc8(acc[ai][bj][m][0], acc[ai][bj][m][1], 1.0f)); } }
.LBB0_561:
	s_lshl_b32 s20, s61, 8
	s_and_b32 s20, s20, 0x700
	v_or_b32_e32 v0, s20, v163
	s_lshr_b32 s20, s61, 2
	s_and_b32 s20, s20, 0x7ffffe
	v_lshl_add_u32 v165, s58, 8, v160
	v_or_b32_e32 v138, s20, v162
	v_lshlrev_b32_e32 v178, 9, v138
	v_ashrrev_i32_e32 v138, 1, v165
	v_cvt_pk_bf16_f32 v70, v70, v71
	v_cvt_pk_bf16_f32 v71, v72, v73
	v_cvt_pk_bf16_f32 v72, v66, v67
	v_add_u32_e32 v66, 0x80, v165
	v_cvt_pk_bf16_f32 v54, v54, v55
	v_cvt_pk_bf16_f32 v55, v56, v57
	v_cvt_pk_bf16_f32 v56, v50, v51
	v_add_u32_e32 v50, 0x90, v165
	v_cvt_pk_bf16_f32 v38, v38, v39
	v_cvt_pk_bf16_f32 v39, v40, v41
	v_cvt_pk_bf16_f32 v40, v34, v35
	v_add_u32_e32 v34, 0xa0, v165
	v_cvt_pk_bf16_f32 v22, v22, v23
	v_cvt_pk_bf16_f32 v23, v24, v25
	v_cvt_pk_bf16_f32 v24, v18, v19
	v_add_u32_e32 v18, 0xb0, v165
	v_add_u32_e32 v138, v138, v178
	v_ashrrev_i32_e32 v66, 1, v66
	v_ashrrev_i32_e32 v50, 1, v50
	v_ashrrev_i32_e32 v34, 1, v34
	v_ashrrev_i32_e32 v18, 1, v18
	v_cvt_pk_bf16_f32 v118, v118, v119
	v_cvt_pk_bf16_f32 v119, v120, v121
	v_cvt_pk_bf16_f32 v120, v114, v115
	v_add_u32_e32 v114, 8, v138
	v_cvt_pk_bf16_f32 v102, v102, v103
	v_cvt_pk_bf16_f32 v103, v104, v105
	v_cvt_pk_bf16_f32 v104, v98, v99
	v_add_u32_e32 v98, 16, v138
	v_cvt_pk_bf16_f32 v86, v86, v87
	v_cvt_pk_bf16_f32 v87, v88, v89
	v_cvt_pk_bf16_f32 v88, v82, v83
	v_add_u32_e32 v82, 24, v138
	v_add_u32_e32 v66, v66, v178
	v_add_u32_e32 v50, v50, v178
	v_add_u32_e32 v34, v34, v178
	v_add_u32_e32 v18, v18, v178
	v_ashrrev_i32_e32 v139, 31, v138
	v_ashrrev_i32_e32 v115, 31, v114
	v_ashrrev_i32_e32 v99, 31, v98
	v_ashrrev_i32_e32 v83, 31, v82
	v_ashrrev_i32_e32 v67, 31, v66
	v_ashrrev_i32_e32 v51, 31, v50
	v_ashrrev_i32_e32 v35, 31, v34
	v_ashrrev_i32_e32 v19, 31, v18
	v_lshlrev_b64 v[166:167], 12, v[138:139]
	v_lshlrev_b64 v[114:115], 12, v[114:115]
	v_lshlrev_b64 v[98:99], 12, v[98:99]
	v_lshlrev_b64 v[82:83], 12, v[82:83]
	v_lshlrev_b64 v[66:67], 12, v[66:67]
	v_lshlrev_b64 v[50:51], 12, v[50:51]
	v_lshlrev_b64 v[34:35], 12, v[34:35]
	v_lshlrev_b64 v[18:19], 12, v[18:19]
	v_lshl_add_u64 v[166:167], s[6:7], 0, v[166:167]
	v_lshlrev_b32_e32 v0, 1, v0
	v_lshl_add_u64 v[114:115], s[6:7], 0, v[114:115]
	v_lshl_add_u64 v[98:99], s[6:7], 0, v[98:99]
	v_lshl_add_u64 v[82:83], s[6:7], 0, v[82:83]
	v_lshl_add_u64 v[66:67], s[6:7], 0, v[66:67]
	v_lshl_add_u64 v[50:51], s[6:7], 0, v[50:51]
	v_lshl_add_u64 v[34:35], s[6:7], 0, v[34:35]
	v_lshl_add_u64 v[18:19], s[6:7], 0, v[18:19]
	v_lshl_add_u64 v[166:167], v[166:167], 0, v[0:1]
	v_cvt_pk_bf16_f32 v122, v122, v123
	v_cvt_pk_bf16_f32 v123, v124, v125
	v_cvt_pk_bf16_f32 v124, v126, v127
	v_cvt_pk_bf16_f32 v125, v128, v129
	v_cvt_pk_bf16_f32 v121, v116, v117
	v_lshl_add_u64 v[114:115], v[114:115], 0, v[0:1]
	v_cvt_pk_bf16_f32 v110, v110, v111
	v_cvt_pk_bf16_f32 v111, v112, v113
	v_cvt_pk_bf16_f32 v112, v106, v107
	v_cvt_pk_bf16_f32 v113, v108, v109
	v_cvt_pk_bf16_f32 v105, v100, v101
	v_lshl_add_u64 v[98:99], v[98:99], 0, v[0:1]
	v_cvt_pk_bf16_f32 v94, v94, v95
	v_cvt_pk_bf16_f32 v95, v96, v97
	v_cvt_pk_bf16_f32 v96, v90, v91
	v_cvt_pk_bf16_f32 v97, v92, v93
	v_cvt_pk_bf16_f32 v89, v84, v85
	v_lshl_add_u64 v[82:83], v[82:83], 0, v[0:1]
	v_cvt_pk_bf16_f32 v78, v78, v79
	v_cvt_pk_bf16_f32 v79, v80, v81
	v_cvt_pk_bf16_f32 v80, v74, v75
	v_cvt_pk_bf16_f32 v81, v76, v77
	v_cvt_pk_bf16_f32 v73, v68, v69
	v_lshl_add_u64 v[66:67], v[66:67], 0, v[0:1]
	v_cvt_pk_bf16_f32 v62, v62, v63
	v_cvt_pk_bf16_f32 v63, v64, v65
	v_cvt_pk_bf16_f32 v64, v58, v59
	v_cvt_pk_bf16_f32 v65, v60, v61
	v_cvt_pk_bf16_f32 v57, v52, v53
	v_lshl_add_u64 v[50:51], v[50:51], 0, v[0:1]
	v_cvt_pk_bf16_f32 v46, v46, v47
	v_cvt_pk_bf16_f32 v47, v48, v49
	v_cvt_pk_bf16_f32 v48, v42, v43
	v_cvt_pk_bf16_f32 v49, v44, v45
	v_cvt_pk_bf16_f32 v41, v36, v37
	v_lshl_add_u64 v[34:35], v[34:35], 0, v[0:1]
	v_cvt_pk_bf16_f32 v30, v30, v31
	v_cvt_pk_bf16_f32 v31, v32, v33
	v_cvt_pk_bf16_f32 v32, v26, v27
	v_cvt_pk_bf16_f32 v33, v28, v29
	v_cvt_pk_bf16_f32 v25, v20, v21
	v_lshl_add_u64 v[18:19], v[18:19], 0, v[0:1]
	v_cvt_pk_bf16_f32 v14, v14, v15
	v_cvt_pk_bf16_f32 v15, v16, v17
	v_cvt_pk_bf16_f32 v16, v10, v11
	v_cvt_pk_bf16_f32 v17, v12, v13
	v_cvt_pk_bf16_f32 v6, v6, v7
	v_cvt_pk_bf16_f32 v7, v8, v9
	v_cvt_pk_bf16_f32 v8, v2, v3
	v_cvt_pk_bf16_f32 v9, v4, v5
	s_and_b64 vcc, exec, s[2:3]
	s_mov_b64 s[2:3], -1
	flat_store_dwordx4 v[166:167], v[122:125]
	flat_store_dwordx4 v[166:167], v[118:121] offset:256
	flat_store_dwordx4 v[114:115], v[110:113]
	flat_store_dwordx4 v[114:115], v[102:105] offset:256
	flat_store_dwordx4 v[98:99], v[94:97]
	flat_store_dwordx4 v[98:99], v[86:89] offset:256
	flat_store_dwordx4 v[82:83], v[78:81]
	flat_store_dwordx4 v[82:83], v[70:73] offset:256
	flat_store_dwordx4 v[66:67], v[62:65]
	flat_store_dwordx4 v[66:67], v[54:57] offset:256
	flat_store_dwordx4 v[50:51], v[46:49]
	flat_store_dwordx4 v[50:51], v[38:41] offset:256
	flat_store_dwordx4 v[34:35], v[30:33]
	flat_store_dwordx4 v[34:35], v[22:25] offset:256
	flat_store_dwordx4 v[18:19], v[14:17]
	flat_store_dwordx4 v[18:19], v[6:9] offset:256
	s_cbranch_vccnz .LBB0_544
	s_andn2_b64 vcc, exec, s[8:9]
	s_cbranch_vccnz .LBB0_543
	s_barrier
	s_branch .LBB0_543

; __device__ __forceinline__ void nt_store16(void* p, const uint4 v) { __builtin_nontemporal_store((u32x4){v.x, v.y, v.z, v.w}, (u32x4*)p); }
; __device__ __forceinline__ uint4 pack_acc8(const f32x4 a, const f32x4 b, float s) { uint4 w; w.x = cvt_pk_bf16(a[0] * s, a[1] * s); w.y = cvt_pk_bf16(a[2] * s, a[3] * s); w.z = cvt_pk_bf16(b[0] * s, b[1] * s); w.w = cvt_pk_bf16(b[2] * s, b[3] * s); return w; }
;     __device__ __forceinline__ void operator()(AccT acc, const Unit& u, int wr, int wc, int fr, int fq) const {
;     ...
;             for (int m = 0; m < 4; ++m) { const int row = row0 + ai * HALF + m * 16;
; #pragma unroll
;                 for (int bj = 0; bj < 2; ++bj) { const int c = col0 + bj * HALF; const int b = c >> 11, s = c & 2047;
;                     nt_store16(FT + ((size_t)((b * 2 + (row & 1)) * 512 + (row >> 1)) * SEQ_ + s), pack_acc8(acc[ai][bj][m][0], acc[ai][bj][m][1], 1.0f)); } }
.LBB0_594:
	s_lshl_b32 s22, s62, 8
	s_and_b32 s22, s22, 0x700
	v_or_b32_e32 v0, s22, v163
	s_lshr_b32 s22, s62, 2
	s_and_b32 s22, s22, 0x7ffffe
	v_lshl_add_u32 v165, s59, 8, v160
	v_or_b32_e32 v138, s22, v162
	v_lshlrev_b32_e32 v178, 9, v138
	v_ashrrev_i32_e32 v138, 1, v165
	v_cvt_pk_bf16_f32 v70, v70, v71
	v_cvt_pk_bf16_f32 v71, v72, v73
	v_cvt_pk_bf16_f32 v72, v66, v67
	v_add_u32_e32 v66, 0x80, v165
	v_cvt_pk_bf16_f32 v54, v54, v55
	v_cvt_pk_bf16_f32 v55, v56, v57
	v_cvt_pk_bf16_f32 v56, v50, v51
	v_add_u32_e32 v50, 0x90, v165
	v_cvt_pk_bf16_f32 v38, v38, v39
	v_cvt_pk_bf16_f32 v39, v40, v41
	v_cvt_pk_bf16_f32 v40, v34, v35
	v_add_u32_e32 v34, 0xa0, v165
	v_cvt_pk_bf16_f32 v22, v22, v23
	v_cvt_pk_bf16_f32 v23, v24, v25
	v_cvt_pk_bf16_f32 v24, v18, v19
	v_add_u32_e32 v18, 0xb0, v165
	v_add_u32_e32 v138, v138, v178
	v_ashrrev_i32_e32 v66, 1, v66
	v_ashrrev_i32_e32 v50, 1, v50
	v_ashrrev_i32_e32 v34, 1, v34
	v_ashrrev_i32_e32 v18, 1, v18
	v_cvt_pk_bf16_f32 v118, v118, v119
	v_cvt_pk_bf16_f32 v119, v120, v121
	v_cvt_pk_bf16_f32 v120, v114, v115
	v_add_u32_e32 v114, 8, v138
	v_cvt_pk_bf16_f32 v102, v102, v103
	v_cvt_pk_bf16_f32 v103, v104, v105
	v_cvt_pk_bf16_f32 v104, v98, v99
	v_add_u32_e32 v98, 16, v138
	v_cvt_pk_bf16_f32 v86, v86, v87
	v_cvt_pk_bf16_f32 v87, v88, v89
	v_cvt_pk_bf16_f32 v88, v82, v83
	v_add_u32_e32 v82, 24, v138
	v_add_u32_e32 v66, v66, v178
	v_add_u32_e32 v50, v50, v178
	v_add_u32_e32 v34, v34, v178
	v_add_u32_e32 v18, v18, v178
	v_ashrrev_i32_e32 v139, 31, v138
	v_ashrrev_i32_e32 v115, 31, v114
	v_ashrrev_i32_e32 v99, 31, v98
	v_ashrrev_i32_e32 v83, 31, v82
	v_ashrrev_i32_e32 v67, 31, v66
	v_ashrrev_i32_e32 v51, 31, v50
	v_ashrrev_i32_e32 v35, 31, v34
	v_ashrrev_i32_e32 v19, 31, v18
	v_lshlrev_b64 v[166:167], 12, v[138:139]
	v_lshlrev_b64 v[114:115], 12, v[114:115]
	v_lshlrev_b64 v[98:99], 12, v[98:99]
	v_lshlrev_b64 v[82:83], 12, v[82:83]
	v_lshlrev_b64 v[66:67], 12, v[66:67]
	v_lshlrev_b64 v[50:51], 12, v[50:51]
	v_lshlrev_b64 v[34:35], 12, v[34:35]
	v_lshlrev_b64 v[18:19], 12, v[18:19]
	v_lshl_add_u64 v[166:167], s[6:7], 0, v[166:167]
	v_lshlrev_b32_e32 v0, 1, v0
	v_lshl_add_u64 v[114:115], s[6:7], 0, v[114:115]
	v_lshl_add_u64 v[98:99], s[6:7], 0, v[98:99]
	v_lshl_add_u64 v[82:83], s[6:7], 0, v[82:83]
	v_lshl_add_u64 v[66:67], s[6:7], 0, v[66:67]
	v_lshl_add_u64 v[50:51], s[6:7], 0, v[50:51]
	v_lshl_add_u64 v[34:35], s[6:7], 0, v[34:35]
	v_lshl_add_u64 v[18:19], s[6:7], 0, v[18:19]
	v_lshl_add_u64 v[166:167], v[166:167], 0, v[0:1]
	v_cvt_pk_bf16_f32 v122, v122, v123
	v_cvt_pk_bf16_f32 v123, v124, v125
	v_cvt_pk_bf16_f32 v124, v126, v127
	v_cvt_pk_bf16_f32 v125, v128, v129
	v_cvt_pk_bf16_f32 v121, v116, v117
	v_lshl_add_u64 v[114:115], v[114:115], 0, v[0:1]
	v_cvt_pk_bf16_f32 v110, v110, v111
	v_cvt_pk_bf16_f32 v111, v112, v113
	v_cvt_pk_bf16_f32 v112, v106, v107
	v_cvt_pk_bf16_f32 v113, v108, v109
	v_cvt_pk_bf16_f32 v105, v100, v101
	v_lshl_add_u64 v[98:99], v[98:99], 0, v[0:1]
	v_cvt_pk_bf16_f32 v94, v94, v95
	v_cvt_pk_bf16_f32 v95, v96, v97
	v_cvt_pk_bf16_f32 v96, v90, v91
	v_cvt_pk_bf16_f32 v97, v92, v93
	v_cvt_pk_bf16_f32 v89, v84, v85
	v_lshl_add_u64 v[82:83], v[82:83], 0, v[0:1]
	v_cvt_pk_bf16_f32 v78, v78, v79
	v_cvt_pk_bf16_f32 v79, v80, v81
	v_cvt_pk_bf16_f32 v80, v74, v75
	v_cvt_pk_bf16_f32 v81, v76, v77
	v_cvt_pk_bf16_f32 v73, v68, v69
	v_lshl_add_u64 v[66:67], v[66:67], 0, v[0:1]
	v_cvt_pk_bf16_f32 v62, v62, v63
	v_cvt_pk_bf16_f32 v63, v64, v65
	v_cvt_pk_bf16_f32 v64, v58, v59
	v_cvt_pk_bf16_f32 v65, v60, v61
	v_cvt_pk_bf16_f32 v57, v52, v53
	v_lshl_add_u64 v[50:51], v[50:51], 0, v[0:1]
	v_cvt_pk_bf16_f32 v46, v46, v47
	v_cvt_pk_bf16_f32 v47, v48, v49
	v_cvt_pk_bf16_f32 v48, v42, v43
	v_cvt_pk_bf16_f32 v49, v44, v45
	v_cvt_pk_bf16_f32 v41, v36, v37
	v_lshl_add_u64 v[34:35], v[34:35], 0, v[0:1]
	v_cvt_pk_bf16_f32 v30, v30, v31
	v_cvt_pk_bf16_f32 v31, v32, v33
	v_cvt_pk_bf16_f32 v32, v26, v27
	v_cvt_pk_bf16_f32 v33, v28, v29
	v_cvt_pk_bf16_f32 v25, v20, v21
	v_lshl_add_u64 v[18:19], v[18:19], 0, v[0:1]
	v_cvt_pk_bf16_f32 v14, v14, v15
	v_cvt_pk_bf16_f32 v15, v16, v17
	v_cvt_pk_bf16_f32 v16, v10, v11
	v_cvt_pk_bf16_f32 v17, v12, v13
	v_cvt_pk_bf16_f32 v6, v6, v7
	v_cvt_pk_bf16_f32 v7, v8, v9
	v_cvt_pk_bf16_f32 v8, v2, v3
	v_cvt_pk_bf16_f32 v9, v4, v5
	s_and_b64 vcc, exec, s[2:3]
	s_mov_b64 s[2:3], -1
	flat_store_dwordx4 v[166:167], v[122:125]
	flat_store_dwordx4 v[166:167], v[118:121] offset:256
	flat_store_dwordx4 v[114:115], v[110:113]
	flat_store_dwordx4 v[114:115], v[102:105] offset:256
	flat_store_dwordx4 v[98:99], v[94:97]
	flat_store_dwordx4 v[98:99], v[86:89] offset:256
	flat_store_dwordx4 v[82:83], v[78:81]
	flat_store_dwordx4 v[82:83], v[70:73] offset:256
	flat_store_dwordx4 v[66:67], v[62:65]
	flat_store_dwordx4 v[66:67], v[54:57] offset:256
	flat_store_dwordx4 v[50:51], v[46:49]
	flat_store_dwordx4 v[50:51], v[38:41] offset:256
	flat_store_dwordx4 v[34:35], v[30:33]
	flat_store_dwordx4 v[34:35], v[22:25] offset:256
	flat_store_dwordx4 v[18:19], v[14:17]
	flat_store_dwordx4 v[18:19], v[6:9] offset:256
	s_cbranch_vccnz .LBB0_576
	s_andn2_b64 vcc, exec, s[12:13]
	s_cbranch_vccnz .LBB0_575
	s_barrier
	s_branch .LBB0_575

; __device__ __forceinline__ float sigmoid_(float x) { return __builtin_amdgcn_rcpf(1.0f + __expf(-x)); }
; __device__ __forceinline__ uint4 pack8(const float (&f)[8]) { uint4 r; r.x = cvt_pk_bf16(f[0], f[1]); r.y = cvt_pk_bf16(f[2], f[3]); r.z = cvt_pk_bf16(f[4], f[5]); r.w = cvt_pk_bf16(f[6], f[7]); return r; }
; __device__ __forceinline__ void nt_store16(void* p, const uint4 v) { __builtin_nontemporal_store((u32x4){v.x, v.y, v.z, v.w}, (u32x4*)p); }
;     __device__ __forceinline__ void operator()(AccT acc, const Unit& u, int wr, int wc, int fr, int fq) const {
;     ...
;                 bf16_t* rowp = O + (size_t)(row0 + ai * HALF + m * 16) * FF_ + col0;
;                 float o[8];
; #pragma unroll
;                 for (int n = 0; n < 2; ++n)
; #pragma unroll
;                     for (int j = 0; j < 4; ++j) { const float gt = acc[ai][0][m][n][j], up = acc[ai][1][m][n][j]; o[n * 4 + j] = gt * sigmoid_(gt) * up; }
;                 nt_store16(rowp, pack8(o));
.LBB0_657:
	v_mul_f32_e32 v138, 0xbfb8aa3b, v126
	v_exp_f32_e32 v138, v138
	v_mul_f32_e32 v139, 0xbfb8aa3b, v127
	v_exp_f32_e32 v139, v139
	v_readlane_b32 s18, v254, 35
	v_add_f32_e32 v138, 1.0, v138
	v_rcp_f32_e32 v180, v138
	v_add_f32_e32 v138, 1.0, v139
	v_rcp_f32_e32 v181, v138
	v_mul_f32_e32 v138, 0xbfb8aa3b, v128
	v_mul_f32_e32 v139, 0xbfb8aa3b, v129
	v_exp_f32_e32 v138, v138
	v_exp_f32_e32 v139, v139
	v_pk_mul_f32 v[126:127], v[126:127], v[180:181]
	v_lshl_or_b32 v166, s59, 7, v162
	v_pk_mul_f32 v[122:123], v[122:123], v[126:127]
	v_add_f32_e32 v126, 1.0, v138
	v_add_f32_e32 v127, 1.0, v139
	v_mul_f32_e32 v138, 0xbfb8aa3b, v118
	v_rcp_f32_e32 v126, v126
	v_rcp_f32_e32 v127, v127
	v_exp_f32_e32 v138, v138
	v_mul_f32_e32 v139, 0xbfb8aa3b, v119
	v_exp_f32_e32 v139, v139
	v_pk_mul_f32 v[126:127], v[128:129], v[126:127]
	v_add_f32_e32 v128, 1.0, v138
	v_mul_f32_e32 v138, 0xbfb8aa3b, v120
	v_add_f32_e32 v129, 1.0, v139
	v_exp_f32_e32 v138, v138
	v_mul_f32_e32 v139, 0xbfb8aa3b, v121
	v_exp_f32_e32 v139, v139
	v_rcp_f32_e32 v128, v128
	v_add_f32_e32 v138, 1.0, v138
	v_rcp_f32_e32 v129, v129
	v_rcp_f32_e32 v180, v138
	v_add_f32_e32 v138, 1.0, v139
	v_rcp_f32_e32 v181, v138
	v_pk_mul_f32 v[118:119], v[118:119], v[128:129]
	v_readlane_b32 s19, v254, 36
	v_pk_mul_f32 v[118:119], v[114:115], v[118:119]
	v_pk_mul_f32 v[114:115], v[120:121], v[180:181]
	v_cvt_pk_bf16_f32 v118, v118, v119
	v_pk_mul_f32 v[120:121], v[116:117], v[114:115]
	v_lshl_add_u32 v164, s58, 8, v160
	v_cvt_pk_bf16_f32 v119, v120, v121
	v_mul_f32_e32 v120, 0xbfb8aa3b, v110
	v_mul_f32_e32 v121, 0xbfb8aa3b, v111
	v_exp_f32_e32 v120, v120
	v_exp_f32_e32 v121, v121
	v_ashrrev_i32_e32 v167, 31, v166
	v_mov_b64_e32 v[158:159], s[18:19]
	v_mad_i64_i32 v[182:183], s[18:19], v164, s67, v[158:159]
	v_pk_mul_f32 v[124:125], v[124:125], v[126:127]
	v_lshlrev_b64 v[114:115], 1, v[166:167]
	v_lshl_add_u64 v[126:127], v[182:183], 0, v[114:115]
	v_cvt_pk_bf16_f32 v116, v122, v123
	v_cvt_pk_bf16_f32 v117, v124, v125
	flat_store_dwordx4 v[126:127], v[116:119]
	s_and_b64 vcc, exec, s[2:3]
	s_mov_b64 s[2:3], -1
	v_add_f32_e32 v116, 1.0, v120
	v_add_f32_e32 v117, 1.0, v121
	v_rcp_f32_e32 v116, v116
	v_rcp_f32_e32 v117, v117
	v_or_b32_e32 v118, 16, v164
	v_mad_i64_i32 v[118:119], s[18:19], v118, s67, v[158:159]
	v_pk_mul_f32 v[110:111], v[110:111], v[116:117]
	v_mul_f32_e32 v116, 0xbfb8aa3b, v112
	v_mul_f32_e32 v117, 0xbfb8aa3b, v113
	v_exp_f32_e32 v116, v116
	v_exp_f32_e32 v117, v117
	v_pk_mul_f32 v[106:107], v[106:107], v[110:111]
	v_add_f32_e32 v110, 1.0, v116
	v_add_f32_e32 v111, 1.0, v117
	v_mul_f32_e32 v116, 0xbfb8aa3b, v102
	v_mul_f32_e32 v117, 0xbfb8aa3b, v103
	v_rcp_f32_e32 v110, v110
	v_rcp_f32_e32 v111, v111
	v_exp_f32_e32 v116, v116
	v_exp_f32_e32 v117, v117
	v_pk_mul_f32 v[110:111], v[112:113], v[110:111]
	v_add_f32_e32 v112, 1.0, v116
	v_add_f32_e32 v113, 1.0, v117
	v_mul_f32_e32 v116, 0xbfb8aa3b, v104
	v_mul_f32_e32 v117, 0xbfb8aa3b, v105
	v_exp_f32_e32 v116, v116
	v_exp_f32_e32 v117, v117
	v_rcp_f32_e32 v112, v112
	v_rcp_f32_e32 v113, v113
	v_add_f32_e32 v116, 1.0, v116
	v_add_f32_e32 v117, 1.0, v117
	v_rcp_f32_e32 v116, v116
	v_rcp_f32_e32 v117, v117
	v_pk_mul_f32 v[102:103], v[102:103], v[112:113]
	v_pk_mul_f32 v[108:109], v[108:109], v[110:111]
	v_pk_mul_f32 v[102:103], v[98:99], v[102:103]
	v_pk_mul_f32 v[98:99], v[104:105], v[116:117]
	v_lshl_add_u64 v[110:111], v[118:119], 0, v[114:115]
	v_pk_mul_f32 v[104:105], v[100:101], v[98:99]
	v_cvt_pk_bf16_f32 v100, v102, v103
	v_mul_f32_e32 v102, 0xbfb8aa3b, v94
	v_mul_f32_e32 v103, 0xbfb8aa3b, v95
	v_exp_f32_e32 v102, v102
	v_exp_f32_e32 v103, v103
	v_cvt_pk_bf16_f32 v98, v106, v107
	v_cvt_pk_bf16_f32 v99, v108, v109
	v_cvt_pk_bf16_f32 v101, v104, v105
	flat_store_dwordx4 v[110:111], v[98:101]
	s_nop 1
	v_add_f32_e32 v98, 1.0, v102
	v_add_f32_e32 v99, 1.0, v103
	v_rcp_f32_e32 v98, v98
	v_rcp_f32_e32 v99, v99
	v_or_b32_e32 v100, 32, v164
	v_mad_i64_i32 v[100:101], s[18:19], v100, s67, v[158:159]
	v_pk_mul_f32 v[94:95], v[94:95], v[98:99]
	v_mul_f32_e32 v98, 0xbfb8aa3b, v96
	v_mul_f32_e32 v99, 0xbfb8aa3b, v97
	v_exp_f32_e32 v98, v98
	v_exp_f32_e32 v99, v99
	v_pk_mul_f32 v[90:91], v[90:91], v[94:95]
	v_add_f32_e32 v94, 1.0, v98
	v_add_f32_e32 v95, 1.0, v99
	v_mul_f32_e32 v98, 0xbfb8aa3b, v86
	v_mul_f32_e32 v99, 0xbfb8aa3b, v87
	v_rcp_f32_e32 v94, v94
	v_rcp_f32_e32 v95, v95
	v_exp_f32_e32 v98, v98
	v_exp_f32_e32 v99, v99
	v_pk_mul_f32 v[94:95], v[96:97], v[94:95]
	v_add_f32_e32 v96, 1.0, v98
	v_add_f32_e32 v97, 1.0, v99
	v_mul_f32_e32 v98, 0xbfb8aa3b, v88
	v_mul_f32_e32 v99, 0xbfb8aa3b, v89
	v_exp_f32_e32 v98, v98
	v_exp_f32_e32 v99, v99
	v_rcp_f32_e32 v96, v96
	v_rcp_f32_e32 v97, v97
	v_add_f32_e32 v98, 1.0, v98
	v_add_f32_e32 v99, 1.0, v99
	v_rcp_f32_e32 v98, v98
	v_rcp_f32_e32 v99, v99
	v_pk_mul_f32 v[86:87], v[86:87], v[96:97]
	v_pk_mul_f32 v[92:93], v[92:93], v[94:95]
	v_pk_mul_f32 v[86:87], v[82:83], v[86:87]
	v_pk_mul_f32 v[82:83], v[88:89], v[98:99]
	v_lshl_add_u64 v[94:95], v[100:101], 0, v[114:115]
	v_pk_mul_f32 v[88:89], v[84:85], v[82:83]
	v_cvt_pk_bf16_f32 v84, v86, v87
	v_mul_f32_e32 v86, 0xbfb8aa3b, v78
	v_mul_f32_e32 v87, 0xbfb8aa3b, v79
	v_exp_f32_e32 v86, v86
	v_exp_f32_e32 v87, v87
	v_cvt_pk_bf16_f32 v82, v90, v91
	v_cvt_pk_bf16_f32 v83, v92, v93
	v_cvt_pk_bf16_f32 v85, v88, v89
	flat_store_dwordx4 v[94:95], v[82:85]
	s_nop 1
	v_add_f32_e32 v82, 1.0, v86
	v_add_f32_e32 v83, 1.0, v87
	v_rcp_f32_e32 v82, v82
	v_rcp_f32_e32 v83, v83
	v_or_b32_e32 v84, 48, v164
	v_mad_i64_i32 v[84:85], s[18:19], v84, s67, v[158:159]
	v_pk_mul_f32 v[78:79], v[78:79], v[82:83]
	v_mul_f32_e32 v82, 0xbfb8aa3b, v80
	v_mul_f32_e32 v83, 0xbfb8aa3b, v81
; __device__ __forceinline__ float sigmoid_(float x) { return __builtin_amdgcn_rcpf(1.0f + __expf(-x)); }
; __device__ __forceinline__ uint4 pack8(const float (&f)[8]) { uint4 r; r.x = cvt_pk_bf16(f[0], f[1]); r.y = cvt_pk_bf16(f[2], f[3]); r.z = cvt_pk_bf16(f[4], f[5]); r.w = cvt_pk_bf16(f[6], f[7]); return r; }
; __device__ __forceinline__ void nt_store16(void* p, const uint4 v) { __builtin_nontemporal_store((u32x4){v.x, v.y, v.z, v.w}, (u32x4*)p); }
;     __device__ __forceinline__ void operator()(AccT acc, const Unit& u, int wr, int wc, int fr, int fq) const {
;     ...
;                 bf16_t* rowp = O + (size_t)(row0 + ai * HALF + m * 16) * FF_ + col0;
;                 float o[8];
; #pragma unroll
;                 for (int n = 0; n < 2; ++n)
; #pragma unroll
;                     for (int j = 0; j < 4; ++j) { const float gt = acc[ai][0][m][n][j], up = acc[ai][1][m][n][j]; o[n * 4 + j] = gt * sigmoid_(gt) * up; }
;                 nt_store16(rowp, pack8(o));
	v_exp_f32_e32 v82, v82
	v_exp_f32_e32 v83, v83
	v_pk_mul_f32 v[74:75], v[74:75], v[78:79]
	v_add_f32_e32 v78, 1.0, v82
	v_add_f32_e32 v79, 1.0, v83
	v_mul_f32_e32 v82, 0xbfb8aa3b, v70
	v_mul_f32_e32 v83, 0xbfb8aa3b, v71
	v_rcp_f32_e32 v78, v78
	v_rcp_f32_e32 v79, v79
	v_exp_f32_e32 v82, v82
	v_exp_f32_e32 v83, v83
	v_pk_mul_f32 v[78:79], v[80:81], v[78:79]
	v_add_f32_e32 v80, 1.0, v82
	v_add_f32_e32 v81, 1.0, v83
	v_mul_f32_e32 v82, 0xbfb8aa3b, v72
	v_mul_f32_e32 v83, 0xbfb8aa3b, v73
	v_exp_f32_e32 v82, v82
	v_exp_f32_e32 v83, v83
	v_rcp_f32_e32 v80, v80
	v_rcp_f32_e32 v81, v81
	v_add_f32_e32 v82, 1.0, v82
	v_add_f32_e32 v83, 1.0, v83
	v_rcp_f32_e32 v82, v82
	v_rcp_f32_e32 v83, v83
	v_pk_mul_f32 v[70:71], v[70:71], v[80:81]
	v_pk_mul_f32 v[76:77], v[76:77], v[78:79]
	v_pk_mul_f32 v[70:71], v[66:67], v[70:71]
	v_pk_mul_f32 v[66:67], v[72:73], v[82:83]
	v_lshl_add_u64 v[78:79], v[84:85], 0, v[114:115]
	v_pk_mul_f32 v[72:73], v[68:69], v[66:67]
	v_cvt_pk_bf16_f32 v68, v70, v71
	v_mul_f32_e32 v70, 0xbfb8aa3b, v62
	v_mul_f32_e32 v71, 0xbfb8aa3b, v63
	v_exp_f32_e32 v70, v70
	v_exp_f32_e32 v71, v71
	v_cvt_pk_bf16_f32 v66, v74, v75
	v_cvt_pk_bf16_f32 v67, v76, v77
	v_cvt_pk_bf16_f32 v69, v72, v73
	flat_store_dwordx4 v[78:79], v[66:69]
	s_nop 1
	v_add_f32_e32 v66, 1.0, v70
	v_add_f32_e32 v67, 1.0, v71
	v_rcp_f32_e32 v66, v66
	v_rcp_f32_e32 v67, v67
	v_add_u32_e32 v68, 0x80, v164
	v_mad_i64_i32 v[68:69], s[18:19], v68, s67, v[158:159]
	v_pk_mul_f32 v[62:63], v[62:63], v[66:67]
	v_mul_f32_e32 v66, 0xbfb8aa3b, v64
	v_mul_f32_e32 v67, 0xbfb8aa3b, v65
	v_exp_f32_e32 v66, v66
	v_exp_f32_e32 v67, v67
	v_pk_mul_f32 v[58:59], v[58:59], v[62:63]
	v_add_f32_e32 v62, 1.0, v66
	v_add_f32_e32 v63, 1.0, v67
	v_mul_f32_e32 v66, 0xbfb8aa3b, v54
	v_mul_f32_e32 v67, 0xbfb8aa3b, v55
	v_rcp_f32_e32 v62, v62
	v_rcp_f32_e32 v63, v63
	v_exp_f32_e32 v66, v66
	v_exp_f32_e32 v67, v67
	v_pk_mul_f32 v[62:63], v[64:65], v[62:63]
	v_add_f32_e32 v64, 1.0, v66
	v_add_f32_e32 v65, 1.0, v67
	v_mul_f32_e32 v66, 0xbfb8aa3b, v56
	v_mul_f32_e32 v67, 0xbfb8aa3b, v57
	v_exp_f32_e32 v66, v66
	v_exp_f32_e32 v67, v67
	v_rcp_f32_e32 v64, v64
	v_rcp_f32_e32 v65, v65
	v_add_f32_e32 v66, 1.0, v66
	v_add_f32_e32 v67, 1.0, v67
	v_rcp_f32_e32 v66, v66
	v_rcp_f32_e32 v67, v67
	v_pk_mul_f32 v[54:55], v[54:55], v[64:65]
	v_pk_mul_f32 v[60:61], v[60:61], v[62:63]
	v_pk_mul_f32 v[54:55], v[50:51], v[54:55]
	v_pk_mul_f32 v[50:51], v[56:57], v[66:67]
	v_lshl_add_u64 v[62:63], v[68:69], 0, v[114:115]
	v_pk_mul_f32 v[56:57], v[52:53], v[50:51]
	v_cvt_pk_bf16_f32 v52, v54, v55
	v_mul_f32_e32 v54, 0xbfb8aa3b, v46
	v_mul_f32_e32 v55, 0xbfb8aa3b, v47
	v_exp_f32_e32 v54, v54
	v_exp_f32_e32 v55, v55
	v_cvt_pk_bf16_f32 v50, v58, v59
	v_cvt_pk_bf16_f32 v51, v60, v61
	v_cvt_pk_bf16_f32 v53, v56, v57
	flat_store_dwordx4 v[62:63], v[50:53]
	s_nop 1
	v_add_f32_e32 v50, 1.0, v54
	v_add_f32_e32 v51, 1.0, v55
	v_rcp_f32_e32 v50, v50
	v_rcp_f32_e32 v51, v51
	v_add_u32_e32 v52, 0x90, v164
	v_mad_i64_i32 v[52:53], s[18:19], v52, s67, v[158:159]
	v_pk_mul_f32 v[46:47], v[46:47], v[50:51]
	v_mul_f32_e32 v50, 0xbfb8aa3b, v48
	v_mul_f32_e32 v51, 0xbfb8aa3b, v49
	v_exp_f32_e32 v50, v50
	v_exp_f32_e32 v51, v51
	v_pk_mul_f32 v[42:43], v[42:43], v[46:47]
	v_add_f32_e32 v46, 1.0, v50
	v_add_f32_e32 v47, 1.0, v51
	v_mul_f32_e32 v50, 0xbfb8aa3b, v38
	v_mul_f32_e32 v51, 0xbfb8aa3b, v39
	v_rcp_f32_e32 v46, v46
	v_rcp_f32_e32 v47, v47
	v_exp_f32_e32 v50, v50
	v_exp_f32_e32 v51, v51
	v_pk_mul_f32 v[46:47], v[48:49], v[46:47]
	v_add_f32_e32 v48, 1.0, v50
	v_add_f32_e32 v49, 1.0, v51
	v_mul_f32_e32 v50, 0xbfb8aa3b, v40
	v_mul_f32_e32 v51, 0xbfb8aa3b, v41
	v_exp_f32_e32 v50, v50
	v_exp_f32_e32 v51, v51
	v_rcp_f32_e32 v48, v48
	v_rcp_f32_e32 v49, v49
	v_add_f32_e32 v50, 1.0, v50
; __device__ __forceinline__ float sigmoid_(float x) { return __builtin_amdgcn_rcpf(1.0f + __expf(-x)); }
; __device__ __forceinline__ uint4 pack8(const float (&f)[8]) { uint4 r; r.x = cvt_pk_bf16(f[0], f[1]); r.y = cvt_pk_bf16(f[2], f[3]); r.z = cvt_pk_bf16(f[4], f[5]); r.w = cvt_pk_bf16(f[6], f[7]); return r; }
; __device__ __forceinline__ void nt_store16(void* p, const uint4 v) { __builtin_nontemporal_store((u32x4){v.x, v.y, v.z, v.w}, (u32x4*)p); }
;     __device__ __forceinline__ void operator()(AccT acc, const Unit& u, int wr, int wc, int fr, int fq) const {
;     ...
;                 bf16_t* rowp = O + (size_t)(row0 + ai * HALF + m * 16) * FF_ + col0;
;                 float o[8];
; #pragma unroll
;                 for (int n = 0; n < 2; ++n)
; #pragma unroll
;                     for (int j = 0; j < 4; ++j) { const float gt = acc[ai][0][m][n][j], up = acc[ai][1][m][n][j]; o[n * 4 + j] = gt * sigmoid_(gt) * up; }
;                 nt_store16(rowp, pack8(o));
	v_add_f32_e32 v51, 1.0, v51
	v_rcp_f32_e32 v50, v50
	v_rcp_f32_e32 v51, v51
	v_pk_mul_f32 v[38:39], v[38:39], v[48:49]
	v_pk_mul_f32 v[44:45], v[44:45], v[46:47]
	v_pk_mul_f32 v[38:39], v[34:35], v[38:39]
	v_pk_mul_f32 v[34:35], v[40:41], v[50:51]
	v_lshl_add_u64 v[46:47], v[52:53], 0, v[114:115]
	v_pk_mul_f32 v[40:41], v[36:37], v[34:35]
	v_cvt_pk_bf16_f32 v36, v38, v39
	v_mul_f32_e32 v38, 0xbfb8aa3b, v30
	v_mul_f32_e32 v39, 0xbfb8aa3b, v31
	v_exp_f32_e32 v38, v38
	v_exp_f32_e32 v39, v39
	v_cvt_pk_bf16_f32 v34, v42, v43
	v_cvt_pk_bf16_f32 v35, v44, v45
	v_cvt_pk_bf16_f32 v37, v40, v41
	flat_store_dwordx4 v[46:47], v[34:37]
	s_nop 1
	v_add_f32_e32 v34, 1.0, v38
	v_add_f32_e32 v35, 1.0, v39
	v_rcp_f32_e32 v34, v34
	v_rcp_f32_e32 v35, v35
	v_add_u32_e32 v36, 0xa0, v164
	v_mad_i64_i32 v[36:37], s[18:19], v36, s67, v[158:159]
	v_pk_mul_f32 v[30:31], v[30:31], v[34:35]
	v_mul_f32_e32 v34, 0xbfb8aa3b, v32
	v_mul_f32_e32 v35, 0xbfb8aa3b, v33
	v_exp_f32_e32 v34, v34
	v_exp_f32_e32 v35, v35
	v_pk_mul_f32 v[26:27], v[26:27], v[30:31]
	v_add_f32_e32 v30, 1.0, v34
	v_add_f32_e32 v31, 1.0, v35
	v_mul_f32_e32 v34, 0xbfb8aa3b, v22
	v_mul_f32_e32 v35, 0xbfb8aa3b, v23
	v_rcp_f32_e32 v30, v30
	v_rcp_f32_e32 v31, v31
	v_exp_f32_e32 v34, v34
	v_exp_f32_e32 v35, v35
	v_pk_mul_f32 v[30:31], v[32:33], v[30:31]
	v_add_f32_e32 v32, 1.0, v34
	v_add_f32_e32 v33, 1.0, v35
	v_mul_f32_e32 v34, 0xbfb8aa3b, v24
	v_mul_f32_e32 v35, 0xbfb8aa3b, v25
	v_exp_f32_e32 v34, v34
	v_exp_f32_e32 v35, v35
	v_rcp_f32_e32 v32, v32
	v_rcp_f32_e32 v33, v33
	v_add_f32_e32 v34, 1.0, v34
	v_add_f32_e32 v35, 1.0, v35
	v_rcp_f32_e32 v34, v34
	v_rcp_f32_e32 v35, v35
	v_pk_mul_f32 v[22:23], v[22:23], v[32:33]
	v_pk_mul_f32 v[28:29], v[28:29], v[30:31]
	v_pk_mul_f32 v[22:23], v[18:19], v[22:23]
	v_pk_mul_f32 v[18:19], v[24:25], v[34:35]
	v_lshl_add_u64 v[30:31], v[36:37], 0, v[114:115]
	v_pk_mul_f32 v[24:25], v[20:21], v[18:19]
	v_cvt_pk_bf16_f32 v20, v22, v23
	v_mul_f32_e32 v22, 0xbfb8aa3b, v14
	v_mul_f32_e32 v23, 0xbfb8aa3b, v15
	v_exp_f32_e32 v22, v22
	v_exp_f32_e32 v23, v23
	v_cvt_pk_bf16_f32 v18, v26, v27
	v_cvt_pk_bf16_f32 v19, v28, v29
	v_cvt_pk_bf16_f32 v21, v24, v25
	flat_store_dwordx4 v[30:31], v[18:21]
	s_nop 1
	v_add_f32_e32 v18, 1.0, v22
	v_add_f32_e32 v19, 1.0, v23
	v_rcp_f32_e32 v18, v18
	v_rcp_f32_e32 v19, v19
	v_add_u32_e32 v20, 0xb0, v164
	v_mad_i64_i32 v[20:21], s[18:19], v20, s67, v[158:159]
	v_pk_mul_f32 v[14:15], v[14:15], v[18:19]
	v_mul_f32_e32 v18, 0xbfb8aa3b, v16
	v_mul_f32_e32 v19, 0xbfb8aa3b, v17
	v_exp_f32_e32 v18, v18
	v_exp_f32_e32 v19, v19
	v_pk_mul_f32 v[10:11], v[10:11], v[14:15]
	v_add_f32_e32 v14, 1.0, v18
	v_add_f32_e32 v15, 1.0, v19
	v_mul_f32_e32 v18, 0xbfb8aa3b, v6
	v_mul_f32_e32 v19, 0xbfb8aa3b, v7
	v_rcp_f32_e32 v14, v14
	v_rcp_f32_e32 v15, v15
	v_exp_f32_e32 v18, v18
	v_exp_f32_e32 v19, v19
	v_pk_mul_f32 v[14:15], v[16:17], v[14:15]
	v_add_f32_e32 v16, 1.0, v18
	v_add_f32_e32 v17, 1.0, v19
	v_mul_f32_e32 v18, 0xbfb8aa3b, v8
	v_mul_f32_e32 v19, 0xbfb8aa3b, v9
	v_exp_f32_e32 v18, v18
	v_exp_f32_e32 v19, v19
	v_rcp_f32_e32 v16, v16
	v_rcp_f32_e32 v17, v17
	v_add_f32_e32 v18, 1.0, v18
	v_add_f32_e32 v19, 1.0, v19
	v_rcp_f32_e32 v18, v18
	v_rcp_f32_e32 v19, v19
	v_pk_mul_f32 v[6:7], v[6:7], v[16:17]
	v_pk_mul_f32 v[12:13], v[12:13], v[14:15]
	v_pk_mul_f32 v[6:7], v[2:3], v[6:7]
	v_pk_mul_f32 v[2:3], v[8:9], v[18:19]
	v_lshl_add_u64 v[14:15], v[20:21], 0, v[114:115]
	v_pk_mul_f32 v[8:9], v[4:5], v[2:3]
	v_cvt_pk_bf16_f32 v2, v10, v11
	v_cvt_pk_bf16_f32 v3, v12, v13
	v_cvt_pk_bf16_f32 v4, v6, v7
	v_cvt_pk_bf16_f32 v5, v8, v9
	flat_store_dwordx4 v[14:15], v[2:5]
	s_cbranch_vccnz .LBB0_645
	s_andn2_b64 vcc, exec, s[10:11]
	s_cbranch_vccnz .LBB0_644
	s_barrier
	s_branch .LBB0_644
